# P3 conv rows fetched in one go + next unit prefetched; P5 transpose load pipelined; intra-chunk kz/Q fetches batched; split-K tail gate values hoisted out of the atomic chain
# speedup vs baseline: 1.0391x; 1.0089x over previous
.LBB0_328:
	s_or_b64 exec, exec, s[0:1]
	s_add_u32 s52, s62, 0x2100000
	s_addc_u32 s53, s63, 0
	s_waitcnt vmcnt(3)
	v_mov_b32_e32 v0, v170
	s_cmpk_gt_i32 s64, 0x20f
	s_waitcnt lgkmcnt(0)
	s_barrier
	s_cbranch_scc1 .LBB0_344
	v_readlane_b32 s8, v251, 2
	s_waitcnt vmcnt(0)
	v_add_u32_e32 v16, 0x400, v0
	v_ashrrev_i32_e32 v1, 31, v0
	v_readlane_b32 s9, v251, 3
	v_readlane_b32 s10, v251, 4
	v_readlane_b32 s11, v251, 5
	v_add_u32_e32 v8, 0x600, v0
	v_add_u32_e32 v10, 0xc00, v0
	v_add_u32_e32 v12, 0x800, v0
	v_add_u32_e32 v14, 0xe00, v0
	v_ashrrev_i32_e32 v17, 31, v16
	v_add_u32_e32 v20, 0xa00, v0
	v_add_u32_e32 v22, 0x1000, v0
	s_movk_i32 s2, 0x84
	v_lshl_add_u64 v[2:3], v[0:1], 1, s[40:41]
	s_movk_i32 s0, 0x1000
	s_mov_b32 s6, 2
	v_lshlrev_b64 v[6:7], 2, v[0:1]
	v_readlane_b32 s16, v251, 10
	v_readlane_b32 s17, v251, 11
	v_readlane_b32 s18, v251, 12
	v_readlane_b32 s19, v251, 13
	v_readlane_b32 s20, v251, 14
	v_readlane_b32 s21, v251, 15
	v_readlane_b32 s22, v251, 16
	v_ashrrev_i32_e32 v9, 31, v8
	v_ashrrev_i32_e32 v11, 31, v10
	v_ashrrev_i32_e32 v13, 31, v12
	v_ashrrev_i32_e32 v15, 31, v14
	v_lshlrev_b64 v[18:19], 2, v[16:17]
	v_ashrrev_i32_e32 v21, 31, v20
	v_ashrrev_i32_e32 v23, 31, v22
	v_mul_lo_u32 v1, v0, s2
	s_mov_b32 s8, 4
	s_mov_b32 s10, 6
	v_lshl_add_u32 v60, v0, 5, v0
	v_cmp_gt_i32_e64 s[0:1], s0, v0
	s_mov_b32 s7, 3
	v_lshl_add_u64 v[4:5], s[18:19], 0, v[6:7]
	v_lshl_add_u64 v[6:7], s[16:17], 0, v[6:7]
	v_lshl_add_u64 v[8:9], v[8:9], 2, s[16:17]
	v_lshl_add_u64 v[10:11], v[10:11], 2, s[16:17]
	v_lshl_add_u64 v[12:13], v[12:13], 2, s[16:17]
	v_lshl_add_u64 v[14:15], v[14:15], 2, s[16:17]
	v_lshl_add_u64 v[16:17], s[18:19], 0, v[18:19]
	v_lshl_add_u64 v[18:19], s[16:17], 0, v[18:19]
	v_lshl_add_u64 v[20:21], v[20:21], 2, s[16:17]
	v_lshl_add_u64 v[22:23], v[22:23], 2, s[16:17]
	v_add_u32_e32 v1, 16, v1
	s_mov_b32 s9, 5
	s_lshl_b32 s16, s64, 5
	s_lshl_b32 s17, s74, 5
	v_lshlrev_b32_e32 v61, 2, v0
	s_movk_i32 s18, 0x2000
	v_mov_b32_e32 v62, 0xc00
	s_mov_b32 s11, 7
	s_movk_i32 s19, 0x4200
	v_mov_b32_e32 v25, 0
	s_movk_i32 s20, 0x7fff
	s_movk_i32 s21, 0xdff
	v_mov_b32_e32 v63, 1
	s_mov_b32 s22, s64
	v_readlane_b32 s12, v251, 6
	v_readlane_b32 s13, v251, 7
	v_readlane_b32 s14, v251, 8
	v_readlane_b32 s15, v251, 9
	v_readlane_b32 s23, v251, 17
	global_load_dword v41, v[4:5], off
	global_load_dword v43, v[4:5], off offset:2048
	global_load_dword v42, v[16:17], off
	global_load_dword v45, v[6:7], off
	global_load_dword v47, v[8:9], off
	global_load_dword v49, v[10:11], off
	global_load_dword v40, v[6:7], off offset:2048
	global_load_dword v52, v[12:13], off
	global_load_dword v53, v[14:15], off
	global_load_dword v44, v[18:19], off
	global_load_dword v46, v[20:21], off
	global_load_dword v48, v[22:23], off
	v_lshlrev_b32_e32 v50, 1, v0
	v_add_u32_e32 v51, 0x10800, v1
	s_lshl_b32 s26, s22, 5
	s_mul_hi_i32 s2, s26, 0x3e0f83e1
	s_lshr_b32 s3, s2, 31
	s_ashr_i32 s2, s2, 11
	s_add_i32 s2, s2, s3
	s_mulk_i32 s2, 0x2100
	s_sub_i32 s23, s26, s2
	s_cmp_lg_u32 s23, 0
	s_cselect_b32 s2, 1, 0
	s_cmp_lg_u32 s23, 0x2000
	s_cselect_b32 s3, 1, 0
	s_and_b32 s24, s2, s3
	s_add_i32 s25, s23, 32
	s_cmp_lg_u32 s25, 0x2000
	s_cselect_b32 s2, 1, 0
	s_cmp_lg_u32 s25, 0x2100
	s_cselect_b32 s3, 1, 0
	s_and_b32 s25, s2, s3
	s_sub_i32 s2, s26, s24
	s_mul_i32 s4, s2, 0xc00
	s_add_u32 s4, s40, s4
	s_addc_u32 s5, s41, 0
	global_load_ushort v64, v50, s[4:5]
	global_load_ushort v65, v50, s[4:5] offset:1024
	global_load_ushort v66, v50, s[4:5] offset:2048
	s_mul_i32 s2, s24, 0xc00
	s_add_u32 s4, s4, s2
	s_addc_u32 s5, s5, 0
	global_load_ushort v67, v50, s[4:5]
	global_load_ushort v68, v50, s[4:5] offset:1024
	global_load_ushort v69, v50, s[4:5] offset:2048
	s_add_u32 s4, s4, 0xc00
	s_addc_u32 s5, s5, 0
	global_load_ushort v70, v50, s[4:5]
	global_load_ushort v71, v50, s[4:5] offset:1024
	global_load_ushort v72, v50, s[4:5] offset:2048
	s_add_u32 s4, s4, 0xc00
	s_addc_u32 s5, s5, 0
	global_load_ushort v73, v50, s[4:5]
	global_load_ushort v74, v50, s[4:5] offset:1024
	global_load_ushort v75, v50, s[4:5] offset:2048
	s_add_u32 s4, s4, 0xc00
	s_addc_u32 s5, s5, 0
	global_load_ushort v76, v50, s[4:5]
	global_load_ushort v77, v50, s[4:5] offset:1024
	global_load_ushort v78, v50, s[4:5] offset:2048
	s_add_u32 s4, s4, 0xc00
	s_addc_u32 s5, s5, 0
	global_load_ushort v79, v50, s[4:5]
	global_load_ushort v80, v50, s[4:5] offset:1024
	global_load_ushort v81, v50, s[4:5] offset:2048
	s_add_u32 s4, s4, 0xc00
	s_addc_u32 s5, s5, 0
	global_load_ushort v82, v50, s[4:5]
	global_load_ushort v83, v50, s[4:5] offset:1024
	global_load_ushort v84, v50, s[4:5] offset:2048
	s_add_u32 s4, s4, 0xc00
	s_addc_u32 s5, s5, 0
	global_load_ushort v85, v50, s[4:5]
	global_load_ushort v86, v50, s[4:5] offset:1024
	global_load_ushort v87, v50, s[4:5] offset:2048
	s_add_u32 s4, s4, 0xc00
	s_addc_u32 s5, s5, 0
	global_load_ushort v88, v50, s[4:5]
	global_load_ushort v89, v50, s[4:5] offset:1024
	global_load_ushort v90, v50, s[4:5] offset:2048
	s_add_u32 s4, s4, 0xc00
	s_addc_u32 s5, s5, 0
	global_load_ushort v91, v50, s[4:5]
	global_load_ushort v92, v50, s[4:5] offset:1024
	global_load_ushort v93, v50, s[4:5] offset:2048
	s_add_u32 s4, s4, 0xc00
	s_addc_u32 s5, s5, 0
	global_load_ushort v94, v50, s[4:5]
	global_load_ushort v95, v50, s[4:5] offset:1024
	global_load_ushort v96, v50, s[4:5] offset:2048
	s_add_u32 s4, s4, 0xc00
	s_addc_u32 s5, s5, 0
	global_load_ushort v97, v50, s[4:5]
	global_load_ushort v98, v50, s[4:5] offset:1024
	global_load_ushort v99, v50, s[4:5] offset:2048
	s_add_u32 s4, s4, 0xc00
	s_addc_u32 s5, s5, 0
	global_load_ushort v100, v50, s[4:5]
	global_load_ushort v101, v50, s[4:5] offset:1024
	global_load_ushort v102, v50, s[4:5] offset:2048
	s_add_u32 s4, s4, 0xc00
	s_addc_u32 s5, s5, 0
	global_load_ushort v103, v50, s[4:5]
	global_load_ushort v104, v50, s[4:5] offset:1024
	global_load_ushort v105, v50, s[4:5] offset:2048
	s_add_u32 s4, s4, 0xc00
	s_addc_u32 s5, s5, 0
	global_load_ushort v106, v50, s[4:5]
	global_load_ushort v107, v50, s[4:5] offset:1024
	global_load_ushort v108, v50, s[4:5] offset:2048
	s_add_u32 s4, s4, 0xc00
	s_addc_u32 s5, s5, 0
	global_load_ushort v109, v50, s[4:5]
	global_load_ushort v110, v50, s[4:5] offset:1024
	global_load_ushort v111, v50, s[4:5] offset:2048
	s_add_u32 s4, s4, 0xc00
	s_addc_u32 s5, s5, 0
	global_load_ushort v112, v50, s[4:5]
	global_load_ushort v113, v50, s[4:5] offset:1024
	global_load_ushort v114, v50, s[4:5] offset:2048
	s_add_u32 s4, s4, 0xc00
	s_addc_u32 s5, s5, 0
	global_load_ushort v115, v50, s[4:5]
	global_load_ushort v116, v50, s[4:5] offset:1024
	global_load_ushort v117, v50, s[4:5] offset:2048
	s_add_u32 s4, s4, 0xc00
	s_addc_u32 s5, s5, 0
	global_load_ushort v118, v50, s[4:5]
	global_load_ushort v119, v50, s[4:5] offset:1024
	global_load_ushort v120, v50, s[4:5] offset:2048
	s_add_u32 s4, s4, 0xc00
	s_addc_u32 s5, s5, 0
	global_load_ushort v121, v50, s[4:5]
	global_load_ushort v122, v50, s[4:5] offset:1024
	global_load_ushort v123, v50, s[4:5] offset:2048
	s_add_u32 s4, s4, 0xc00
	s_addc_u32 s5, s5, 0
	global_load_ushort v124, v50, s[4:5]
	global_load_ushort v125, v50, s[4:5] offset:1024
	global_load_ushort v126, v50, s[4:5] offset:2048
	s_add_u32 s4, s4, 0xc00
	s_addc_u32 s5, s5, 0
	global_load_ushort v127, v50, s[4:5]
	global_load_ushort v128, v50, s[4:5] offset:1024
	global_load_ushort v129, v50, s[4:5] offset:2048
	s_add_u32 s4, s4, 0xc00
	s_addc_u32 s5, s5, 0
	global_load_ushort v130, v50, s[4:5]
	global_load_ushort v131, v50, s[4:5] offset:1024
	global_load_ushort v132, v50, s[4:5] offset:2048
	s_add_u32 s4, s4, 0xc00
	s_addc_u32 s5, s5, 0
	global_load_ushort v133, v50, s[4:5]
	global_load_ushort v134, v50, s[4:5] offset:1024
	global_load_ushort v135, v50, s[4:5] offset:2048
	s_add_u32 s4, s4, 0xc00
	s_addc_u32 s5, s5, 0
	global_load_ushort v136, v50, s[4:5]
	global_load_ushort v137, v50, s[4:5] offset:1024
	global_load_ushort v138, v50, s[4:5] offset:2048
	s_add_u32 s4, s4, 0xc00
	s_addc_u32 s5, s5, 0
	global_load_ushort v139, v50, s[4:5]
	global_load_ushort v140, v50, s[4:5] offset:1024
	global_load_ushort v141, v50, s[4:5] offset:2048
	s_add_u32 s4, s4, 0xc00
	s_addc_u32 s5, s5, 0
	global_load_ushort v142, v50, s[4:5]
	global_load_ushort v143, v50, s[4:5] offset:1024
	global_load_ushort v144, v50, s[4:5] offset:2048
	s_add_u32 s4, s4, 0xc00
	s_addc_u32 s5, s5, 0
	global_load_ushort v145, v50, s[4:5]
	global_load_ushort v146, v50, s[4:5] offset:1024
	global_load_ushort v147, v50, s[4:5] offset:2048
	s_add_u32 s4, s4, 0xc00
	s_addc_u32 s5, s5, 0
	global_load_ushort v148, v50, s[4:5]
	global_load_ushort v149, v50, s[4:5] offset:1024
	global_load_ushort v150, v50, s[4:5] offset:2048
	s_add_u32 s4, s4, 0xc00
	s_addc_u32 s5, s5, 0
	global_load_ushort v151, v50, s[4:5]
	global_load_ushort v152, v50, s[4:5] offset:1024
	global_load_ushort v153, v50, s[4:5] offset:2048
	s_add_u32 s4, s4, 0xc00
	s_addc_u32 s5, s5, 0
	global_load_ushort v154, v50, s[4:5]
	global_load_ushort v155, v50, s[4:5] offset:1024
	global_load_ushort v156, v50, s[4:5] offset:2048
	s_add_u32 s4, s4, 0xc00
	s_addc_u32 s5, s5, 0
	global_load_ushort v157, v50, s[4:5]
	global_load_ushort v158, v50, s[4:5] offset:1024
	global_load_ushort v159, v50, s[4:5] offset:2048
	s_add_u32 s4, s4, 0xc00
	s_addc_u32 s5, s5, 0
	global_load_ushort v160, v50, s[4:5]
	global_load_ushort v161, v50, s[4:5] offset:1024
	global_load_ushort v162, v50, s[4:5] offset:2048
	s_mul_i32 s2, s25, 0xc00
	s_add_u32 s4, s4, s2
	s_addc_u32 s5, s5, 0
	global_load_ushort v163, v50, s[4:5]
	global_load_ushort v164, v50, s[4:5] offset:1024
	global_load_ushort v165, v50, s[4:5] offset:2048
	s_waitcnt vmcnt(0)
	s_branch .LBB0_331

.LBB0_331:
	s_lshl_b32 s12, s22, 5
	s_mul_hi_i32 s2, s12, 0x3e0f83e1
	s_lshr_b32 s3, s2, 31
	s_ashr_i32 s2, s2, 11
	s_add_i32 s2, s2, s3
	s_mulk_i32 s2, 0x2100
	s_sub_i32 s23, s12, s2
	s_ashr_i32 s13, s12, 31
	s_cmp_lg_u32 s23, 0
	s_cselect_b32 s2, 1, 0
	s_cmp_lg_u32 s23, 0x2000
	s_cselect_b32 s3, 1, 0
	s_and_b32 s24, s2, s3
	s_add_i32 s25, s23, 32
	s_cmp_lg_u32 s25, 0x2000
	s_cselect_b32 s2, 1, 0
	s_cmp_lg_u32 s25, 0x2100
	s_cselect_b32 s3, 1, 0
	s_and_b32 s25, s2, s3
	s_cmp_lg_u32 s24, 0
	s_cselect_b64 s[14:15], -1, 0
	s_cmp_lg_u32 s25, 0
	s_cselect_b64 s[2:3], -1, 0
	s_barrier
	s_waitcnt vmcnt(8)
	v_lshlrev_b32_e32 v64, 16, v64
	v_lshlrev_b32_e32 v65, 16, v65
	v_lshlrev_b32_e32 v66, 16, v66
	v_lshlrev_b32_e32 v67, 16, v67
	v_lshlrev_b32_e32 v68, 16, v68
	v_lshlrev_b32_e32 v69, 16, v69
	v_lshlrev_b32_e32 v70, 16, v70
	v_lshlrev_b32_e32 v71, 16, v71
	v_lshlrev_b32_e32 v72, 16, v72
	v_lshlrev_b32_e32 v73, 16, v73
	v_lshlrev_b32_e32 v74, 16, v74
	v_lshlrev_b32_e32 v75, 16, v75
	v_lshlrev_b32_e32 v76, 16, v76
	v_lshlrev_b32_e32 v77, 16, v77
	v_lshlrev_b32_e32 v78, 16, v78
	v_lshlrev_b32_e32 v79, 16, v79
	v_lshlrev_b32_e32 v80, 16, v80
	v_lshlrev_b32_e32 v81, 16, v81
	v_lshlrev_b32_e32 v82, 16, v82
	v_lshlrev_b32_e32 v83, 16, v83
	v_lshlrev_b32_e32 v84, 16, v84
	v_lshlrev_b32_e32 v85, 16, v85
	v_lshlrev_b32_e32 v86, 16, v86
	v_lshlrev_b32_e32 v87, 16, v87
	v_lshlrev_b32_e32 v88, 16, v88
	v_lshlrev_b32_e32 v89, 16, v89
	v_lshlrev_b32_e32 v90, 16, v90
	v_lshlrev_b32_e32 v91, 16, v91
	v_lshlrev_b32_e32 v92, 16, v92
	v_lshlrev_b32_e32 v93, 16, v93
	v_lshlrev_b32_e32 v94, 16, v94
	v_lshlrev_b32_e32 v95, 16, v95
	v_lshlrev_b32_e32 v96, 16, v96
	v_lshlrev_b32_e32 v97, 16, v97
	v_lshlrev_b32_e32 v98, 16, v98
	v_lshlrev_b32_e32 v99, 16, v99
	v_lshlrev_b32_e32 v100, 16, v100
	v_lshlrev_b32_e32 v101, 16, v101
	v_lshlrev_b32_e32 v102, 16, v102
	v_lshlrev_b32_e32 v103, 16, v103
	v_lshlrev_b32_e32 v104, 16, v104
	v_lshlrev_b32_e32 v105, 16, v105
	v_lshlrev_b32_e32 v106, 16, v106
	v_lshlrev_b32_e32 v107, 16, v107
	v_lshlrev_b32_e32 v108, 16, v108
	v_lshlrev_b32_e32 v109, 16, v109
	v_lshlrev_b32_e32 v110, 16, v110
	v_lshlrev_b32_e32 v111, 16, v111
	v_lshlrev_b32_e32 v112, 16, v112
	v_lshlrev_b32_e32 v113, 16, v113
	v_lshlrev_b32_e32 v114, 16, v114
	v_lshlrev_b32_e32 v115, 16, v115
	v_lshlrev_b32_e32 v116, 16, v116
	v_lshlrev_b32_e32 v117, 16, v117
	v_lshlrev_b32_e32 v118, 16, v118
	v_lshlrev_b32_e32 v119, 16, v119
	v_lshlrev_b32_e32 v120, 16, v120
	v_lshlrev_b32_e32 v121, 16, v121
	v_lshlrev_b32_e32 v122, 16, v122
	v_lshlrev_b32_e32 v123, 16, v123
	v_lshlrev_b32_e32 v124, 16, v124
	v_lshlrev_b32_e32 v125, 16, v125
	v_lshlrev_b32_e32 v126, 16, v126
	v_lshlrev_b32_e32 v127, 16, v127
	v_lshlrev_b32_e32 v128, 16, v128
	v_lshlrev_b32_e32 v129, 16, v129
	v_lshlrev_b32_e32 v130, 16, v130
	v_lshlrev_b32_e32 v131, 16, v131
	v_lshlrev_b32_e32 v132, 16, v132
	v_lshlrev_b32_e32 v133, 16, v133
	v_lshlrev_b32_e32 v134, 16, v134
	v_lshlrev_b32_e32 v135, 16, v135
	v_lshlrev_b32_e32 v136, 16, v136
	v_lshlrev_b32_e32 v137, 16, v137
	v_lshlrev_b32_e32 v138, 16, v138
	v_lshlrev_b32_e32 v139, 16, v139
	v_lshlrev_b32_e32 v140, 16, v140
	v_lshlrev_b32_e32 v141, 16, v141
	v_lshlrev_b32_e32 v142, 16, v142
	v_lshlrev_b32_e32 v143, 16, v143
	v_lshlrev_b32_e32 v144, 16, v144
	v_lshlrev_b32_e32 v145, 16, v145
	v_lshlrev_b32_e32 v146, 16, v146
	v_lshlrev_b32_e32 v147, 16, v147
	v_lshlrev_b32_e32 v148, 16, v148
	v_lshlrev_b32_e32 v149, 16, v149
	v_lshlrev_b32_e32 v150, 16, v150
	v_lshlrev_b32_e32 v151, 16, v151
	v_lshlrev_b32_e32 v152, 16, v152
	v_lshlrev_b32_e32 v153, 16, v153
	v_lshlrev_b32_e32 v154, 16, v154
	v_lshlrev_b32_e32 v155, 16, v155
	v_lshlrev_b32_e32 v156, 16, v156
	v_lshlrev_b32_e32 v157, 16, v157
	v_lshlrev_b32_e32 v158, 16, v158
	v_lshlrev_b32_e32 v159, 16, v159
	v_lshlrev_b32_e32 v160, 16, v160
	v_lshlrev_b32_e32 v161, 16, v161
	v_lshlrev_b32_e32 v162, 16, v162
	v_lshlrev_b32_e32 v163, 16, v163
	v_lshlrev_b32_e32 v164, 16, v164
	v_lshlrev_b32_e32 v165, 16, v165
	v_cndmask_b32_e64 v64, 0, v64, s[14:15]
	v_cndmask_b32_e64 v65, 0, v65, s[14:15]
	v_cndmask_b32_e64 v66, 0, v66, s[14:15]
	v_cndmask_b32_e64 v163, 0, v163, s[2:3]
	v_cndmask_b32_e64 v164, 0, v164, s[2:3]
	v_cndmask_b32_e64 v165, 0, v165, s[2:3]
	v_mul_f32_e32 v64, v64, v45
	v_fmac_f32_e32 v64, v67, v47
	v_fmac_f32_e32 v64, v70, v49
	v_add_f32_e32 v64, v41, v64
	v_mul_f32_e32 v65, v65, v40
	v_fmac_f32_e32 v65, v68, v52
	v_fmac_f32_e32 v65, v71, v53
	v_add_f32_e32 v65, v43, v65
	v_mul_f32_e32 v66, v66, v44
	v_fmac_f32_e32 v66, v69, v46
	v_fmac_f32_e32 v66, v72, v48
	v_add_f32_e32 v66, v42, v66
	v_mul_f32_e32 v66, v66, v65
	v_mul_f32_e32 v67, v67, v45
	v_fmac_f32_e32 v67, v70, v47
	v_fmac_f32_e32 v67, v73, v49
	v_add_f32_e32 v67, v41, v67
	v_mul_f32_e32 v68, v68, v40
	v_fmac_f32_e32 v68, v71, v52
	v_fmac_f32_e32 v68, v74, v53
	v_add_f32_e32 v68, v43, v68
	v_mul_f32_e32 v69, v69, v44
	v_fmac_f32_e32 v69, v72, v46
	v_fmac_f32_e32 v69, v75, v48
	v_add_f32_e32 v69, v42, v69
	v_mul_f32_e32 v69, v69, v68
	ds_write2_b32 v1, v66, v69 offset0:0 offset1:1
	ds_write2_b32 v51, v64, v67 offset0:0 offset1:1
	v_mul_f32_e32 v70, v70, v45
	v_fmac_f32_e32 v70, v73, v47
	v_fmac_f32_e32 v70, v76, v49
	v_add_f32_e32 v70, v41, v70
	v_mul_f32_e32 v71, v71, v40
	v_fmac_f32_e32 v71, v74, v52
	v_fmac_f32_e32 v71, v77, v53
	v_add_f32_e32 v71, v43, v71
	v_mul_f32_e32 v72, v72, v44
	v_fmac_f32_e32 v72, v75, v46
	v_fmac_f32_e32 v72, v78, v48
	v_add_f32_e32 v72, v42, v72
	v_mul_f32_e32 v72, v72, v71
	v_mul_f32_e32 v73, v73, v45
	v_fmac_f32_e32 v73, v76, v47
	v_fmac_f32_e32 v73, v79, v49
	v_add_f32_e32 v73, v41, v73
	v_mul_f32_e32 v74, v74, v40
	v_fmac_f32_e32 v74, v77, v52
	v_fmac_f32_e32 v74, v80, v53
	v_add_f32_e32 v74, v43, v74
	v_mul_f32_e32 v75, v75, v44
	v_fmac_f32_e32 v75, v78, v46
	v_fmac_f32_e32 v75, v81, v48
	v_add_f32_e32 v75, v42, v75
	v_mul_f32_e32 v75, v75, v74
	ds_write2_b32 v1, v72, v75 offset0:2 offset1:3
	ds_write2_b32 v51, v70, v73 offset0:2 offset1:3
	v_mul_f32_e32 v76, v76, v45
	v_fmac_f32_e32 v76, v79, v47
	v_fmac_f32_e32 v76, v82, v49
	v_add_f32_e32 v76, v41, v76
	v_mul_f32_e32 v77, v77, v40
	v_fmac_f32_e32 v77, v80, v52
	v_fmac_f32_e32 v77, v83, v53
	v_add_f32_e32 v77, v43, v77
	v_mul_f32_e32 v78, v78, v44
	v_fmac_f32_e32 v78, v81, v46
	v_fmac_f32_e32 v78, v84, v48
	v_add_f32_e32 v78, v42, v78
	v_mul_f32_e32 v78, v78, v77
	v_mul_f32_e32 v79, v79, v45
	v_fmac_f32_e32 v79, v82, v47
	v_fmac_f32_e32 v79, v85, v49
	v_add_f32_e32 v79, v41, v79
	v_mul_f32_e32 v80, v80, v40
	v_fmac_f32_e32 v80, v83, v52
	v_fmac_f32_e32 v80, v86, v53
	v_add_f32_e32 v80, v43, v80
	v_mul_f32_e32 v81, v81, v44
	v_fmac_f32_e32 v81, v84, v46
	v_fmac_f32_e32 v81, v87, v48
	v_add_f32_e32 v81, v42, v81
	v_mul_f32_e32 v81, v81, v80
	ds_write2_b32 v1, v78, v81 offset0:4 offset1:5
	ds_write2_b32 v51, v76, v79 offset0:4 offset1:5
	v_mul_f32_e32 v82, v82, v45
	v_fmac_f32_e32 v82, v85, v47
	v_fmac_f32_e32 v82, v88, v49
	v_add_f32_e32 v82, v41, v82
	v_mul_f32_e32 v83, v83, v40
	v_fmac_f32_e32 v83, v86, v52
	v_fmac_f32_e32 v83, v89, v53
	v_add_f32_e32 v83, v43, v83
	v_mul_f32_e32 v84, v84, v44
	v_fmac_f32_e32 v84, v87, v46
	v_fmac_f32_e32 v84, v90, v48
	v_add_f32_e32 v84, v42, v84
	v_mul_f32_e32 v84, v84, v83
	v_mul_f32_e32 v85, v85, v45
	v_fmac_f32_e32 v85, v88, v47
	v_fmac_f32_e32 v85, v91, v49
	v_add_f32_e32 v85, v41, v85
	v_mul_f32_e32 v86, v86, v40
	v_fmac_f32_e32 v86, v89, v52
	v_fmac_f32_e32 v86, v92, v53
	v_add_f32_e32 v86, v43, v86
	v_mul_f32_e32 v87, v87, v44
	v_fmac_f32_e32 v87, v90, v46
	v_fmac_f32_e32 v87, v93, v48
	v_add_f32_e32 v87, v42, v87
	v_mul_f32_e32 v87, v87, v86
	ds_write2_b32 v1, v84, v87 offset0:6 offset1:7
	ds_write2_b32 v51, v82, v85 offset0:6 offset1:7
	v_mul_f32_e32 v88, v88, v45
	v_fmac_f32_e32 v88, v91, v47
	v_fmac_f32_e32 v88, v94, v49
	v_add_f32_e32 v88, v41, v88
	v_mul_f32_e32 v89, v89, v40
	v_fmac_f32_e32 v89, v92, v52
	v_fmac_f32_e32 v89, v95, v53
	v_add_f32_e32 v89, v43, v89
	v_mul_f32_e32 v90, v90, v44
	v_fmac_f32_e32 v90, v93, v46
	v_fmac_f32_e32 v90, v96, v48
	v_add_f32_e32 v90, v42, v90
	v_mul_f32_e32 v90, v90, v89
	v_mul_f32_e32 v91, v91, v45
	v_fmac_f32_e32 v91, v94, v47
	v_fmac_f32_e32 v91, v97, v49
	v_add_f32_e32 v91, v41, v91
	v_mul_f32_e32 v92, v92, v40
	v_fmac_f32_e32 v92, v95, v52
	v_fmac_f32_e32 v92, v98, v53
	v_add_f32_e32 v92, v43, v92
	v_mul_f32_e32 v93, v93, v44
	v_fmac_f32_e32 v93, v96, v46
	v_fmac_f32_e32 v93, v99, v48
	v_add_f32_e32 v93, v42, v93
	v_mul_f32_e32 v93, v93, v92
	ds_write2_b32 v1, v90, v93 offset0:8 offset1:9
	ds_write2_b32 v51, v88, v91 offset0:8 offset1:9
	v_mul_f32_e32 v94, v94, v45
	v_fmac_f32_e32 v94, v97, v47
	v_fmac_f32_e32 v94, v100, v49
	v_add_f32_e32 v94, v41, v94
	v_mul_f32_e32 v95, v95, v40
	v_fmac_f32_e32 v95, v98, v52
	v_fmac_f32_e32 v95, v101, v53
	v_add_f32_e32 v95, v43, v95
	v_mul_f32_e32 v96, v96, v44
	v_fmac_f32_e32 v96, v99, v46
	v_fmac_f32_e32 v96, v102, v48
	v_add_f32_e32 v96, v42, v96
	v_mul_f32_e32 v96, v96, v95
	v_mul_f32_e32 v97, v97, v45
	v_fmac_f32_e32 v97, v100, v47
	v_fmac_f32_e32 v97, v103, v49
	v_add_f32_e32 v97, v41, v97
	v_mul_f32_e32 v98, v98, v40
	v_fmac_f32_e32 v98, v101, v52
	v_fmac_f32_e32 v98, v104, v53
	v_add_f32_e32 v98, v43, v98
	v_mul_f32_e32 v99, v99, v44
	v_fmac_f32_e32 v99, v102, v46
	v_fmac_f32_e32 v99, v105, v48
	v_add_f32_e32 v99, v42, v99
	v_mul_f32_e32 v99, v99, v98
	ds_write2_b32 v1, v96, v99 offset0:10 offset1:11
	ds_write2_b32 v51, v94, v97 offset0:10 offset1:11
	v_mul_f32_e32 v100, v100, v45
	v_fmac_f32_e32 v100, v103, v47
	v_fmac_f32_e32 v100, v106, v49
	v_add_f32_e32 v100, v41, v100
	v_mul_f32_e32 v101, v101, v40
	v_fmac_f32_e32 v101, v104, v52
	v_fmac_f32_e32 v101, v107, v53
	v_add_f32_e32 v101, v43, v101
	v_mul_f32_e32 v102, v102, v44
	v_fmac_f32_e32 v102, v105, v46
	v_fmac_f32_e32 v102, v108, v48
	v_add_f32_e32 v102, v42, v102
	v_mul_f32_e32 v102, v102, v101
	v_mul_f32_e32 v103, v103, v45
	v_fmac_f32_e32 v103, v106, v47
	v_fmac_f32_e32 v103, v109, v49
	v_add_f32_e32 v103, v41, v103
	v_mul_f32_e32 v104, v104, v40
	v_fmac_f32_e32 v104, v107, v52
	v_fmac_f32_e32 v104, v110, v53
	v_add_f32_e32 v104, v43, v104
	v_mul_f32_e32 v105, v105, v44
	v_fmac_f32_e32 v105, v108, v46
	v_fmac_f32_e32 v105, v111, v48
	v_add_f32_e32 v105, v42, v105
	v_mul_f32_e32 v105, v105, v104
	ds_write2_b32 v1, v102, v105 offset0:12 offset1:13
	ds_write2_b32 v51, v100, v103 offset0:12 offset1:13
	v_mul_f32_e32 v106, v106, v45
	v_fmac_f32_e32 v106, v109, v47
	v_fmac_f32_e32 v106, v112, v49
	v_add_f32_e32 v106, v41, v106
	v_mul_f32_e32 v107, v107, v40
	v_fmac_f32_e32 v107, v110, v52
	v_fmac_f32_e32 v107, v113, v53
	v_add_f32_e32 v107, v43, v107
	v_mul_f32_e32 v108, v108, v44
	v_fmac_f32_e32 v108, v111, v46
	v_fmac_f32_e32 v108, v114, v48
	v_add_f32_e32 v108, v42, v108
	v_mul_f32_e32 v108, v108, v107
	v_mul_f32_e32 v109, v109, v45
	v_fmac_f32_e32 v109, v112, v47
	v_fmac_f32_e32 v109, v115, v49
	v_add_f32_e32 v109, v41, v109
	v_mul_f32_e32 v110, v110, v40
	v_fmac_f32_e32 v110, v113, v52
	v_fmac_f32_e32 v110, v116, v53
	v_add_f32_e32 v110, v43, v110
	v_mul_f32_e32 v111, v111, v44
	v_fmac_f32_e32 v111, v114, v46
	v_fmac_f32_e32 v111, v117, v48
	v_add_f32_e32 v111, v42, v111
	v_mul_f32_e32 v111, v111, v110
	ds_write2_b32 v1, v108, v111 offset0:14 offset1:15
	ds_write2_b32 v51, v106, v109 offset0:14 offset1:15
	v_mul_f32_e32 v112, v112, v45
	v_fmac_f32_e32 v112, v115, v47
	v_fmac_f32_e32 v112, v118, v49
	v_add_f32_e32 v112, v41, v112
	v_mul_f32_e32 v113, v113, v40
	v_fmac_f32_e32 v113, v116, v52
	v_fmac_f32_e32 v113, v119, v53
	v_add_f32_e32 v113, v43, v113
	v_mul_f32_e32 v114, v114, v44
	v_fmac_f32_e32 v114, v117, v46
	v_fmac_f32_e32 v114, v120, v48
	v_add_f32_e32 v114, v42, v114
	v_mul_f32_e32 v114, v114, v113
	v_mul_f32_e32 v115, v115, v45
	v_fmac_f32_e32 v115, v118, v47
	v_fmac_f32_e32 v115, v121, v49
	v_add_f32_e32 v115, v41, v115
	v_mul_f32_e32 v116, v116, v40
	v_fmac_f32_e32 v116, v119, v52
	v_fmac_f32_e32 v116, v122, v53
	v_add_f32_e32 v116, v43, v116
	v_mul_f32_e32 v117, v117, v44
	v_fmac_f32_e32 v117, v120, v46
	v_fmac_f32_e32 v117, v123, v48
	v_add_f32_e32 v117, v42, v117
	v_mul_f32_e32 v117, v117, v116
	ds_write2_b32 v1, v114, v117 offset0:16 offset1:17
	ds_write2_b32 v51, v112, v115 offset0:16 offset1:17
	v_mul_f32_e32 v118, v118, v45
	v_fmac_f32_e32 v118, v121, v47
	v_fmac_f32_e32 v118, v124, v49
	v_add_f32_e32 v118, v41, v118
	v_mul_f32_e32 v119, v119, v40
	v_fmac_f32_e32 v119, v122, v52
	v_fmac_f32_e32 v119, v125, v53
	v_add_f32_e32 v119, v43, v119
	v_mul_f32_e32 v120, v120, v44
	v_fmac_f32_e32 v120, v123, v46
	v_fmac_f32_e32 v120, v126, v48
	v_add_f32_e32 v120, v42, v120
	v_mul_f32_e32 v120, v120, v119
	v_mul_f32_e32 v121, v121, v45
	v_fmac_f32_e32 v121, v124, v47
	v_fmac_f32_e32 v121, v127, v49
	v_add_f32_e32 v121, v41, v121
	v_mul_f32_e32 v122, v122, v40
	v_fmac_f32_e32 v122, v125, v52
	v_fmac_f32_e32 v122, v128, v53
	v_add_f32_e32 v122, v43, v122
	v_mul_f32_e32 v123, v123, v44
	v_fmac_f32_e32 v123, v126, v46
	v_fmac_f32_e32 v123, v129, v48
	v_add_f32_e32 v123, v42, v123
	v_mul_f32_e32 v123, v123, v122
	ds_write2_b32 v1, v120, v123 offset0:18 offset1:19
	ds_write2_b32 v51, v118, v121 offset0:18 offset1:19
	v_mul_f32_e32 v124, v124, v45
	v_fmac_f32_e32 v124, v127, v47
	v_fmac_f32_e32 v124, v130, v49
	v_add_f32_e32 v124, v41, v124
	v_mul_f32_e32 v125, v125, v40
	v_fmac_f32_e32 v125, v128, v52
	v_fmac_f32_e32 v125, v131, v53
	v_add_f32_e32 v125, v43, v125
	v_mul_f32_e32 v126, v126, v44
	v_fmac_f32_e32 v126, v129, v46
	v_fmac_f32_e32 v126, v132, v48
	v_add_f32_e32 v126, v42, v126
	v_mul_f32_e32 v126, v126, v125
	v_mul_f32_e32 v127, v127, v45
	v_fmac_f32_e32 v127, v130, v47
	v_fmac_f32_e32 v127, v133, v49
	v_add_f32_e32 v127, v41, v127
	v_mul_f32_e32 v128, v128, v40
	v_fmac_f32_e32 v128, v131, v52
	v_fmac_f32_e32 v128, v134, v53
	v_add_f32_e32 v128, v43, v128
	v_mul_f32_e32 v129, v129, v44
	v_fmac_f32_e32 v129, v132, v46
	v_fmac_f32_e32 v129, v135, v48
	v_add_f32_e32 v129, v42, v129
	v_mul_f32_e32 v129, v129, v128
	ds_write2_b32 v1, v126, v129 offset0:20 offset1:21
	ds_write2_b32 v51, v124, v127 offset0:20 offset1:21
	v_mul_f32_e32 v130, v130, v45
	v_fmac_f32_e32 v130, v133, v47
	v_fmac_f32_e32 v130, v136, v49
	v_add_f32_e32 v130, v41, v130
	v_mul_f32_e32 v131, v131, v40
	v_fmac_f32_e32 v131, v134, v52
	v_fmac_f32_e32 v131, v137, v53
	v_add_f32_e32 v131, v43, v131
	v_mul_f32_e32 v132, v132, v44
	v_fmac_f32_e32 v132, v135, v46
	v_fmac_f32_e32 v132, v138, v48
	v_add_f32_e32 v132, v42, v132
	v_mul_f32_e32 v132, v132, v131
	v_mul_f32_e32 v133, v133, v45
	v_fmac_f32_e32 v133, v136, v47
	v_fmac_f32_e32 v133, v139, v49
	v_add_f32_e32 v133, v41, v133
	v_mul_f32_e32 v134, v134, v40
	v_fmac_f32_e32 v134, v137, v52
	v_fmac_f32_e32 v134, v140, v53
	v_add_f32_e32 v134, v43, v134
	v_mul_f32_e32 v135, v135, v44
	v_fmac_f32_e32 v135, v138, v46
	v_fmac_f32_e32 v135, v141, v48
	v_add_f32_e32 v135, v42, v135
	v_mul_f32_e32 v135, v135, v134
	ds_write2_b32 v1, v132, v135 offset0:22 offset1:23
	ds_write2_b32 v51, v130, v133 offset0:22 offset1:23
	v_mul_f32_e32 v136, v136, v45
	v_fmac_f32_e32 v136, v139, v47
	v_fmac_f32_e32 v136, v142, v49
	v_add_f32_e32 v136, v41, v136
	v_mul_f32_e32 v137, v137, v40
	v_fmac_f32_e32 v137, v140, v52
	v_fmac_f32_e32 v137, v143, v53
	v_add_f32_e32 v137, v43, v137
	v_mul_f32_e32 v138, v138, v44
	v_fmac_f32_e32 v138, v141, v46
	v_fmac_f32_e32 v138, v144, v48
	v_add_f32_e32 v138, v42, v138
	v_mul_f32_e32 v138, v138, v137
	v_mul_f32_e32 v139, v139, v45
	v_fmac_f32_e32 v139, v142, v47
	v_fmac_f32_e32 v139, v145, v49
	v_add_f32_e32 v139, v41, v139
	v_mul_f32_e32 v140, v140, v40
	v_fmac_f32_e32 v140, v143, v52
	v_fmac_f32_e32 v140, v146, v53
	v_add_f32_e32 v140, v43, v140
	v_mul_f32_e32 v141, v141, v44
	v_fmac_f32_e32 v141, v144, v46
	v_fmac_f32_e32 v141, v147, v48
	v_add_f32_e32 v141, v42, v141
	v_mul_f32_e32 v141, v141, v140
	ds_write2_b32 v1, v138, v141 offset0:24 offset1:25
	ds_write2_b32 v51, v136, v139 offset0:24 offset1:25
	v_mul_f32_e32 v142, v142, v45
	v_fmac_f32_e32 v142, v145, v47
	v_fmac_f32_e32 v142, v148, v49
	v_add_f32_e32 v142, v41, v142
	v_mul_f32_e32 v143, v143, v40
	v_fmac_f32_e32 v143, v146, v52
	v_fmac_f32_e32 v143, v149, v53
	v_add_f32_e32 v143, v43, v143
	v_mul_f32_e32 v144, v144, v44
	v_fmac_f32_e32 v144, v147, v46
	v_fmac_f32_e32 v144, v150, v48
	v_add_f32_e32 v144, v42, v144
	v_mul_f32_e32 v144, v144, v143
	v_mul_f32_e32 v145, v145, v45
	v_fmac_f32_e32 v145, v148, v47
	v_fmac_f32_e32 v145, v151, v49
	v_add_f32_e32 v145, v41, v145
	v_mul_f32_e32 v146, v146, v40
	v_fmac_f32_e32 v146, v149, v52
	v_fmac_f32_e32 v146, v152, v53
	v_add_f32_e32 v146, v43, v146
	v_mul_f32_e32 v147, v147, v44
	v_fmac_f32_e32 v147, v150, v46
	v_fmac_f32_e32 v147, v153, v48
	v_add_f32_e32 v147, v42, v147
	v_mul_f32_e32 v147, v147, v146
	ds_write2_b32 v1, v144, v147 offset0:26 offset1:27
	ds_write2_b32 v51, v142, v145 offset0:26 offset1:27
	v_mul_f32_e32 v148, v148, v45
	v_fmac_f32_e32 v148, v151, v47
	v_fmac_f32_e32 v148, v154, v49
	v_add_f32_e32 v148, v41, v148
	v_mul_f32_e32 v149, v149, v40
	v_fmac_f32_e32 v149, v152, v52
	v_fmac_f32_e32 v149, v155, v53
	v_add_f32_e32 v149, v43, v149
	v_mul_f32_e32 v150, v150, v44
	v_fmac_f32_e32 v150, v153, v46
	v_fmac_f32_e32 v150, v156, v48
	v_add_f32_e32 v150, v42, v150
	v_mul_f32_e32 v150, v150, v149
	v_mul_f32_e32 v151, v151, v45
	v_fmac_f32_e32 v151, v154, v47
	v_fmac_f32_e32 v151, v157, v49
	v_add_f32_e32 v151, v41, v151
	v_mul_f32_e32 v152, v152, v40
	v_fmac_f32_e32 v152, v155, v52
	v_fmac_f32_e32 v152, v158, v53
	v_add_f32_e32 v152, v43, v152
	v_mul_f32_e32 v153, v153, v44
	v_fmac_f32_e32 v153, v156, v46
	v_fmac_f32_e32 v153, v159, v48
	v_add_f32_e32 v153, v42, v153
	v_mul_f32_e32 v153, v153, v152
	ds_write2_b32 v1, v150, v153 offset0:28 offset1:29
	ds_write2_b32 v51, v148, v151 offset0:28 offset1:29
	v_mul_f32_e32 v154, v154, v45
	v_fmac_f32_e32 v154, v157, v47
	v_fmac_f32_e32 v154, v160, v49
	v_add_f32_e32 v154, v41, v154
	v_mul_f32_e32 v155, v155, v40
	v_fmac_f32_e32 v155, v158, v52
	v_fmac_f32_e32 v155, v161, v53
	v_add_f32_e32 v155, v43, v155
	v_mul_f32_e32 v156, v156, v44
	v_fmac_f32_e32 v156, v159, v46
	v_fmac_f32_e32 v156, v162, v48
	v_add_f32_e32 v156, v42, v156
	v_mul_f32_e32 v156, v156, v155
	v_mul_f32_e32 v157, v157, v45
	v_fmac_f32_e32 v157, v160, v47
	v_fmac_f32_e32 v157, v163, v49
	v_add_f32_e32 v157, v41, v157
	v_mul_f32_e32 v158, v158, v40
	v_fmac_f32_e32 v158, v161, v52
	v_fmac_f32_e32 v158, v164, v53
	v_add_f32_e32 v158, v43, v158
	v_mul_f32_e32 v159, v159, v44
	v_fmac_f32_e32 v159, v162, v46
	v_fmac_f32_e32 v159, v165, v48
	v_add_f32_e32 v159, v42, v159
	v_mul_f32_e32 v159, v159, v158
	ds_write2_b32 v1, v156, v159 offset0:30 offset1:31
	ds_write2_b32 v51, v154, v157 offset0:30 offset1:31
.LBB0_341:
	s_waitcnt lgkmcnt(0)
	s_barrier
	s_add_i32 s6, s22, s74
	s_cmpk_gt_i32 s6, 0x20f
	s_cbranch_scc1 .Lp3_nonext
	s_lshl_b32 s26, s6, 5
	s_mul_hi_i32 s2, s26, 0x3e0f83e1
	s_lshr_b32 s3, s2, 31
	s_ashr_i32 s2, s2, 11
	s_add_i32 s2, s2, s3
	s_mulk_i32 s2, 0x2100
	s_sub_i32 s23, s26, s2
	s_cmp_lg_u32 s23, 0
	s_cselect_b32 s2, 1, 0
	s_cmp_lg_u32 s23, 0x2000
	s_cselect_b32 s3, 1, 0
	s_and_b32 s24, s2, s3
	s_add_i32 s25, s23, 32
	s_cmp_lg_u32 s25, 0x2000
	s_cselect_b32 s2, 1, 0
	s_cmp_lg_u32 s25, 0x2100
	s_cselect_b32 s3, 1, 0
	s_and_b32 s25, s2, s3
	s_sub_i32 s2, s26, s24
	s_mul_i32 s4, s2, 0xc00
	s_add_u32 s4, s40, s4
	s_addc_u32 s5, s41, 0
	global_load_ushort v64, v50, s[4:5]
	global_load_ushort v65, v50, s[4:5] offset:1024
	global_load_ushort v66, v50, s[4:5] offset:2048
	s_mul_i32 s2, s24, 0xc00
	s_add_u32 s4, s4, s2
	s_addc_u32 s5, s5, 0
	global_load_ushort v67, v50, s[4:5]
	global_load_ushort v68, v50, s[4:5] offset:1024
	global_load_ushort v69, v50, s[4:5] offset:2048
	s_add_u32 s4, s4, 0xc00
	s_addc_u32 s5, s5, 0
	global_load_ushort v70, v50, s[4:5]
	global_load_ushort v71, v50, s[4:5] offset:1024
	global_load_ushort v72, v50, s[4:5] offset:2048
	s_add_u32 s4, s4, 0xc00
	s_addc_u32 s5, s5, 0
	global_load_ushort v73, v50, s[4:5]
	global_load_ushort v74, v50, s[4:5] offset:1024
	global_load_ushort v75, v50, s[4:5] offset:2048
	s_add_u32 s4, s4, 0xc00
	s_addc_u32 s5, s5, 0
	global_load_ushort v76, v50, s[4:5]
	global_load_ushort v77, v50, s[4:5] offset:1024
	global_load_ushort v78, v50, s[4:5] offset:2048
	s_add_u32 s4, s4, 0xc00
	s_addc_u32 s5, s5, 0
	global_load_ushort v79, v50, s[4:5]
	global_load_ushort v80, v50, s[4:5] offset:1024
	global_load_ushort v81, v50, s[4:5] offset:2048
	s_add_u32 s4, s4, 0xc00
	s_addc_u32 s5, s5, 0
	global_load_ushort v82, v50, s[4:5]
	global_load_ushort v83, v50, s[4:5] offset:1024
	global_load_ushort v84, v50, s[4:5] offset:2048
	s_add_u32 s4, s4, 0xc00
	s_addc_u32 s5, s5, 0
	global_load_ushort v85, v50, s[4:5]
	global_load_ushort v86, v50, s[4:5] offset:1024
	global_load_ushort v87, v50, s[4:5] offset:2048
	s_add_u32 s4, s4, 0xc00
	s_addc_u32 s5, s5, 0
	global_load_ushort v88, v50, s[4:5]
	global_load_ushort v89, v50, s[4:5] offset:1024
	global_load_ushort v90, v50, s[4:5] offset:2048
	s_add_u32 s4, s4, 0xc00
	s_addc_u32 s5, s5, 0
	global_load_ushort v91, v50, s[4:5]
	global_load_ushort v92, v50, s[4:5] offset:1024
	global_load_ushort v93, v50, s[4:5] offset:2048
	s_add_u32 s4, s4, 0xc00
	s_addc_u32 s5, s5, 0
	global_load_ushort v94, v50, s[4:5]
	global_load_ushort v95, v50, s[4:5] offset:1024
	global_load_ushort v96, v50, s[4:5] offset:2048
	s_add_u32 s4, s4, 0xc00
	s_addc_u32 s5, s5, 0
	global_load_ushort v97, v50, s[4:5]
	global_load_ushort v98, v50, s[4:5] offset:1024
	global_load_ushort v99, v50, s[4:5] offset:2048
	s_add_u32 s4, s4, 0xc00
	s_addc_u32 s5, s5, 0
	global_load_ushort v100, v50, s[4:5]
	global_load_ushort v101, v50, s[4:5] offset:1024
	global_load_ushort v102, v50, s[4:5] offset:2048
	s_add_u32 s4, s4, 0xc00
	s_addc_u32 s5, s5, 0
	global_load_ushort v103, v50, s[4:5]
	global_load_ushort v104, v50, s[4:5] offset:1024
	global_load_ushort v105, v50, s[4:5] offset:2048
	s_add_u32 s4, s4, 0xc00
	s_addc_u32 s5, s5, 0
	global_load_ushort v106, v50, s[4:5]
	global_load_ushort v107, v50, s[4:5] offset:1024
	global_load_ushort v108, v50, s[4:5] offset:2048
	s_add_u32 s4, s4, 0xc00
	s_addc_u32 s5, s5, 0
	global_load_ushort v109, v50, s[4:5]
	global_load_ushort v110, v50, s[4:5] offset:1024
	global_load_ushort v111, v50, s[4:5] offset:2048
	s_add_u32 s4, s4, 0xc00
	s_addc_u32 s5, s5, 0
	global_load_ushort v112, v50, s[4:5]
	global_load_ushort v113, v50, s[4:5] offset:1024
	global_load_ushort v114, v50, s[4:5] offset:2048
	s_add_u32 s4, s4, 0xc00
	s_addc_u32 s5, s5, 0
	global_load_ushort v115, v50, s[4:5]
	global_load_ushort v116, v50, s[4:5] offset:1024
	global_load_ushort v117, v50, s[4:5] offset:2048
	s_add_u32 s4, s4, 0xc00
	s_addc_u32 s5, s5, 0
	global_load_ushort v118, v50, s[4:5]
	global_load_ushort v119, v50, s[4:5] offset:1024
	global_load_ushort v120, v50, s[4:5] offset:2048
	s_add_u32 s4, s4, 0xc00
	s_addc_u32 s5, s5, 0
	global_load_ushort v121, v50, s[4:5]
	global_load_ushort v122, v50, s[4:5] offset:1024
	global_load_ushort v123, v50, s[4:5] offset:2048
	s_add_u32 s4, s4, 0xc00
	s_addc_u32 s5, s5, 0
	global_load_ushort v124, v50, s[4:5]
	global_load_ushort v125, v50, s[4:5] offset:1024
	global_load_ushort v126, v50, s[4:5] offset:2048
	s_add_u32 s4, s4, 0xc00
	s_addc_u32 s5, s5, 0
	global_load_ushort v127, v50, s[4:5]
	global_load_ushort v128, v50, s[4:5] offset:1024
	global_load_ushort v129, v50, s[4:5] offset:2048
	s_add_u32 s4, s4, 0xc00
	s_addc_u32 s5, s5, 0
	global_load_ushort v130, v50, s[4:5]
	global_load_ushort v131, v50, s[4:5] offset:1024
	global_load_ushort v132, v50, s[4:5] offset:2048
	s_add_u32 s4, s4, 0xc00
	s_addc_u32 s5, s5, 0
	global_load_ushort v133, v50, s[4:5]
	global_load_ushort v134, v50, s[4:5] offset:1024
	global_load_ushort v135, v50, s[4:5] offset:2048
	s_add_u32 s4, s4, 0xc00
	s_addc_u32 s5, s5, 0
	global_load_ushort v136, v50, s[4:5]
	global_load_ushort v137, v50, s[4:5] offset:1024
	global_load_ushort v138, v50, s[4:5] offset:2048
	s_add_u32 s4, s4, 0xc00
	s_addc_u32 s5, s5, 0
	global_load_ushort v139, v50, s[4:5]
	global_load_ushort v140, v50, s[4:5] offset:1024
	global_load_ushort v141, v50, s[4:5] offset:2048
	s_add_u32 s4, s4, 0xc00
	s_addc_u32 s5, s5, 0
	global_load_ushort v142, v50, s[4:5]
	global_load_ushort v143, v50, s[4:5] offset:1024
	global_load_ushort v144, v50, s[4:5] offset:2048
	s_add_u32 s4, s4, 0xc00
	s_addc_u32 s5, s5, 0
	global_load_ushort v145, v50, s[4:5]
	global_load_ushort v146, v50, s[4:5] offset:1024
	global_load_ushort v147, v50, s[4:5] offset:2048
	s_add_u32 s4, s4, 0xc00
	s_addc_u32 s5, s5, 0
	global_load_ushort v148, v50, s[4:5]
	global_load_ushort v149, v50, s[4:5] offset:1024
	global_load_ushort v150, v50, s[4:5] offset:2048
	s_add_u32 s4, s4, 0xc00
	s_addc_u32 s5, s5, 0
	global_load_ushort v151, v50, s[4:5]
	global_load_ushort v152, v50, s[4:5] offset:1024
	global_load_ushort v153, v50, s[4:5] offset:2048
	s_add_u32 s4, s4, 0xc00
	s_addc_u32 s5, s5, 0
	global_load_ushort v154, v50, s[4:5]
	global_load_ushort v155, v50, s[4:5] offset:1024
	global_load_ushort v156, v50, s[4:5] offset:2048
	s_add_u32 s4, s4, 0xc00
	s_addc_u32 s5, s5, 0
	global_load_ushort v157, v50, s[4:5]
	global_load_ushort v158, v50, s[4:5] offset:1024
	global_load_ushort v159, v50, s[4:5] offset:2048
	s_add_u32 s4, s4, 0xc00
	s_addc_u32 s5, s5, 0
	global_load_ushort v160, v50, s[4:5]
	global_load_ushort v161, v50, s[4:5] offset:1024
	global_load_ushort v162, v50, s[4:5] offset:2048
	s_mul_i32 s2, s25, 0xc00
	s_add_u32 s4, s4, s2
	s_addc_u32 s5, s5, 0
	global_load_ushort v163, v50, s[4:5]
	global_load_ushort v164, v50, s[4:5] offset:1024
	global_load_ushort v165, v50, s[4:5] offset:2048
.Lp3_nonext:
	s_and_saveexec_b64 s[2:3], s[0:1]
	s_cbranch_execz .LBB0_330
	s_lshl_b64 s[4:5], s[12:13], 2
	s_add_u32 s4, s62, s4
	s_addc_u32 s5, s63, s5
	s_lshl_b64 s[12:13], s[12:13], 1
	s_add_u32 s12, s52, s12
	s_addc_u32 s13, s53, s13
	s_mov_b64 s[14:15], 0
	v_mov_b32_e32 v26, v61
	v_mov_b32_e32 v27, v0

.LBB0_570:
	s_or_b64 exec, exec, s[0:1]
	v_mov_b32_e32 v0, v170
	s_cmpk_gt_i32 s64, 0x83f
	s_waitcnt lgkmcnt(0)
	s_barrier
	s_cbranch_scc1 .LBB0_573
	s_waitcnt vmcnt(0)
	v_ashrrev_i32_e32 v4, 3, v0
	v_lshlrev_b32_e32 v0, 3, v0
	v_and_b32_e32 v0, 56, v0
	s_movk_i32 s0, 0x84
	v_mul_lo_u32 v2, v4, s0
	v_lshlrev_b32_e32 v3, 1, v0
	v_readlane_b32 s0, v251, 56
	v_add3_u32 v5, 16, v2, v3
	v_mul_u32_u24_e32 v2, 0x84, v0
	v_lshlrev_b32_e32 v3, 1, v4
	v_readlane_b32 s1, v251, 57
	v_mov_b32_e32 v1, 0
	v_add3_u32 v6, 16, v2, v3
	s_lshl_b32 s2, s64, 6
	s_lshl_b32 s3, s78, 6
	s_mov_b32 s4, 0x8400
	v_mov_b64_e32 v[2:3], s[0:1]
	v_lshlrev_b32_e32 v0, 1, v0
	s_mov_b32 s1, 0
	v_readlane_b32 s5, v251, 60
	s_mov_b32 s6, s64
	s_and_b32 s0, s2, 0x1c0
	s_and_b32 s8, s5, 0xffffffc0
	v_add_u32_e32 v7, s0, v4
	s_ashr_i32 s9, s8, 31
	v_mad_i64_i32 v[8:9], s[10:11], v7, s4, v[2:3]
	v_lshl_add_u64 v[8:9], s[8:9], 1, v[8:9]
	v_lshl_add_u64 v[8:9], v[8:9], 0, v[0:1]
	global_load_dwordx4 v[8:11], v[8:9], off
	s_waitcnt vmcnt(0)
.LBB0_572:
	s_and_b32 s0, s2, 0x1c0
	s_and_b32 s8, s5, 0xffffffc0
	v_add_u32_e32 v12, s8, v4
	v_ashrrev_i32_e32 v13, 31, v12
	v_lshlrev_b64 v[12:13], 11, v[12:13]
	s_lshl_b32 s0, s0, 1
	v_lshl_add_u64 v[12:13], s[40:41], 0, v[12:13]
	s_add_i32 s6, s6, s78
	s_add_i32 s2, s2, s3
	s_add_i32 s5, s5, s57
	v_lshl_add_u64 v[12:13], v[12:13], 0, s[0:1]
	v_lshl_add_u64 v[12:13], v[12:13], 0, v[0:1]
	s_barrier
	s_waitcnt vmcnt(1)
	ds_write2_b32 v5, v8, v9 offset1:1
	ds_write2_b32 v5, v10, v11 offset0:2 offset1:3
	s_cmpk_gt_i32 s6, 0x83f
	s_cbranch_scc1 .Ltr5_nopf
	s_and_b32 s0, s2, 0x1c0
	s_and_b32 s8, s5, 0xffffffc0
	v_add_u32_e32 v7, s0, v4
	s_ashr_i32 s9, s8, 31
	v_mad_i64_i32 v[8:9], s[10:11], v7, s4, v[2:3]
	v_lshl_add_u64 v[8:9], s[8:9], 1, v[8:9]
	v_lshl_add_u64 v[8:9], v[8:9], 0, v[0:1]
	global_load_dwordx4 v[8:11], v[8:9], off
.Ltr5_nopf:
	s_waitcnt lgkmcnt(0)
	s_barrier
	ds_read_u16 v7, v6
	ds_read_u16 v14, v6 offset:132
	ds_read_u16 v15, v6 offset:264
	ds_read_u16 v16, v6 offset:396
	s_waitcnt lgkmcnt(2)
	v_lshl_or_b32 v14, v14, 16, v7
	s_waitcnt lgkmcnt(0)
	v_lshl_or_b32 v15, v16, 16, v15
	ds_read_u16 v16, v6 offset:528
	ds_read_u16 v7, v6 offset:660
	ds_read_u16 v17, v6 offset:792
	ds_read_u16 v18, v6 offset:924
	s_waitcnt lgkmcnt(2)
	v_lshl_or_b32 v16, v7, 16, v16
	s_waitcnt lgkmcnt(0)
	v_lshl_or_b32 v17, v18, 16, v17
	global_store_dwordx4 v[12:13], v[14:17], off
	s_cmpk_gt_i32 s6, 0x83f
	s_cbranch_scc0 .LBB0_572

.LBB0_895:
	s_and_b64 vcc, exec, s[0:1]
	s_cbranch_vccz .LBB0_843
	v_add_u32_e32 v116, v142, v141
	v_mul_i32_i24_e32 v112, 0x2100, v116
	v_sub_u32_e32 v118, v140, v112
	v_mul_i32_i24_e32 v112, 0x1800, v116
	v_cmp_gt_i32_e32 vcc, s40, v118
	v_or3_b32 v126, v214, v139, s47
	v_ashrrev_i32_e32 v127, 31, v126
	v_cndmask_b32_e32 v112, v215, v112, vcc
	v_ashrrev_i32_e32 v113, 31, v112
	v_lshl_add_u64 v[112:113], v[112:113], 2, s[76:77]
	v_lshl_add_u64 v[124:125], v[112:113], 0, s[14:15]
	v_lshlrev_b64 v[112:113], 2, v[126:127]
	v_lshl_add_u64 v[114:115], v[124:125], 0, v[112:113]
	global_load_dword v127, v[114:115], off
	v_ashrrev_i32_e32 v117, 2, v138
	v_and_b32_e32 v129, -4, v117
	v_lshl_add_u32 v117, v116, 8, v216
	v_lshlrev_b32_e32 v116, 13, v116
	v_cndmask_b32_e32 v130, v117, v116, vcc
	v_mov_b32_e32 v119, s61
	v_mov_b32_e32 v122, s59
	v_add3_u32 v118, v130, v118, v129
	v_mov_b32_e32 v123, s60
	v_mov_b32_e32 v128, s58
	v_cndmask_b32_e32 v117, v119, v122, vcc
	v_ashrrev_i32_e32 v119, 31, v118
	v_cndmask_b32_e32 v116, v123, v128, vcc
	v_lshlrev_b64 v[122:123], 12, v[118:119]
	v_or_b32_e32 v120, 16, v126
	v_lshl_add_u64 v[122:123], v[116:117], 0, v[122:123]
	v_ashrrev_i32_e32 v121, 31, v120
	v_lshl_add_u64 v[128:129], v[122:123], 0, v[112:113]
	v_lshl_add_u64 v[120:121], v[120:121], 2, v[124:125]
	v_or_b32_e32 v122, 32, v126
	v_ashrrev_i32_e32 v123, 31, v122
	v_lshl_add_u64 v[122:123], v[122:123], 2, v[124:125]
	v_or_b32_e32 v126, 48, v126
	s_waitcnt vmcnt(0)
	v_mul_f32_e32 v108, v108, v127
	global_atomic_add_f32 v[128:129], v108, off
	global_load_dword v108, v[120:121], off
	v_ashrrev_i32_e32 v127, 31, v126
	v_lshl_add_u64 v[124:125], v[126:127], 2, v[124:125]
	global_load_dword v244, v[114:115], off
	global_load_dword v245, v[120:121], off
	global_load_dword v246, v[122:123], off
	global_load_dword v247, v[124:125], off
	v_or_b32_e32 v126, 1, v118
	v_ashrrev_i32_e32 v127, 31, v126
	v_lshlrev_b64 v[126:127], 12, v[126:127]
	v_lshl_add_u64 v[126:127], v[116:117], 0, v[126:127]
	v_lshl_add_u64 v[126:127], v[126:127], 0, v[112:113]
	s_waitcnt vmcnt(0)
	v_mul_f32_e32 v104, v104, v108
	global_atomic_add_f32 v[128:129], v104, off offset:64
	v_mov_b32_e32 v104, v246
	v_mul_f32_e32 v100, v100, v104
	global_atomic_add_f32 v[128:129], v100, off offset:128
	v_mov_b32_e32 v100, v247
	v_mul_f32_e32 v96, v96, v100
	global_atomic_add_f32 v[128:129], v96, off offset:192
	v_mov_b32_e32 v96, v244
	v_mul_f32_e32 v96, v109, v96
	global_atomic_add_f32 v[126:127], v96, off
	v_mov_b32_e32 v96, v245
	v_mul_f32_e32 v96, v105, v96
	global_atomic_add_f32 v[126:127], v96, off offset:64
	v_mov_b32_e32 v96, v246
	v_mul_f32_e32 v96, v101, v96
	global_atomic_add_f32 v[126:127], v96, off offset:128
	v_mov_b32_e32 v96, v247
	v_mul_f32_e32 v96, v97, v96
	global_atomic_add_f32 v[126:127], v96, off offset:192
	v_mov_b32_e32 v100, v244
	v_or_b32_e32 v96, 2, v118
	v_ashrrev_i32_e32 v97, 31, v96
	v_lshlrev_b64 v[96:97], 12, v[96:97]
	v_lshl_add_u64 v[96:97], v[116:117], 0, v[96:97]
	v_lshl_add_u64 v[96:97], v[96:97], 0, v[112:113]
	v_mul_f32_e32 v100, v110, v100
	global_atomic_add_f32 v[96:97], v100, off
	v_mov_b32_e32 v100, v245
	v_mul_f32_e32 v100, v106, v100
	global_atomic_add_f32 v[96:97], v100, off offset:64
	v_mov_b32_e32 v100, v246
	v_mul_f32_e32 v100, v102, v100
	global_atomic_add_f32 v[96:97], v100, off offset:128
	v_mov_b32_e32 v100, v247
	v_mul_f32_e32 v98, v98, v100
	global_atomic_add_f32 v[96:97], v98, off offset:192
	v_mov_b32_e32 v98, v244
	v_or_b32_e32 v96, 3, v118
	v_ashrrev_i32_e32 v97, 31, v96
	v_lshlrev_b64 v[96:97], 12, v[96:97]
	v_lshl_add_u64 v[96:97], v[116:117], 0, v[96:97]
	v_lshl_add_u64 v[96:97], v[96:97], 0, v[112:113]
	v_mul_f32_e32 v98, v111, v98
	global_atomic_add_f32 v[96:97], v98, off
	v_mov_b32_e32 v98, v245
	v_mul_f32_e32 v98, v107, v98
	global_atomic_add_f32 v[96:97], v98, off offset:64
	v_mov_b32_e32 v98, v246
	v_mul_f32_e32 v98, v103, v98
	global_atomic_add_f32 v[96:97], v98, off offset:128
	v_mov_b32_e32 v98, v247
	v_mul_f32_e32 v98, v99, v98
	global_atomic_add_f32 v[96:97], v98, off offset:192
	v_mov_b32_e32 v98, v244
	v_add_u32_e32 v96, 16, v118
	v_ashrrev_i32_e32 v97, 31, v96
	v_lshlrev_b64 v[96:97], 12, v[96:97]
	v_lshl_add_u64 v[96:97], v[116:117], 0, v[96:97]
	v_lshl_add_u64 v[96:97], v[96:97], 0, v[112:113]
	v_mul_f32_e32 v92, v92, v98
	global_atomic_add_f32 v[96:97], v92, off
	v_mov_b32_e32 v92, v245
	v_mul_f32_e32 v88, v88, v92
	global_atomic_add_f32 v[96:97], v88, off offset:64
	v_mov_b32_e32 v88, v246
	v_mul_f32_e32 v84, v84, v88
	global_atomic_add_f32 v[96:97], v84, off offset:128
	v_mov_b32_e32 v84, v247
	v_mul_f32_e32 v80, v80, v84
	global_atomic_add_f32 v[96:97], v80, off offset:192
	v_mov_b32_e32 v80, v244
	v_add_u32_e32 v96, 17, v118
	v_ashrrev_i32_e32 v97, 31, v96
	v_lshlrev_b64 v[96:97], 12, v[96:97]
	v_lshl_add_u64 v[96:97], v[116:117], 0, v[96:97]
	v_lshl_add_u64 v[96:97], v[96:97], 0, v[112:113]
	v_mul_f32_e32 v80, v93, v80
	global_atomic_add_f32 v[96:97], v80, off
	v_mov_b32_e32 v80, v245
	v_mul_f32_e32 v80, v89, v80
	global_atomic_add_f32 v[96:97], v80, off offset:64
	v_mov_b32_e32 v80, v246
	v_mul_f32_e32 v80, v85, v80
	global_atomic_add_f32 v[96:97], v80, off offset:128
	v_mov_b32_e32 v80, v247
	v_mul_f32_e32 v80, v81, v80
	global_atomic_add_f32 v[96:97], v80, off offset:192
	v_mov_b32_e32 v84, v244
	v_add_u32_e32 v80, 18, v118
	v_ashrrev_i32_e32 v81, 31, v80
	v_lshlrev_b64 v[80:81], 12, v[80:81]
	v_lshl_add_u64 v[80:81], v[116:117], 0, v[80:81]
	v_lshl_add_u64 v[80:81], v[80:81], 0, v[112:113]
	v_mul_f32_e32 v84, v94, v84
	global_atomic_add_f32 v[80:81], v84, off
	v_mov_b32_e32 v84, v245
	v_mul_f32_e32 v84, v90, v84
	global_atomic_add_f32 v[80:81], v84, off offset:64
	v_mov_b32_e32 v84, v246
	v_mul_f32_e32 v84, v86, v84
	global_atomic_add_f32 v[80:81], v84, off offset:128
	v_mov_b32_e32 v84, v247
	v_mul_f32_e32 v82, v82, v84
	global_atomic_add_f32 v[80:81], v82, off offset:192
	v_mov_b32_e32 v82, v244
	v_add_u32_e32 v80, 19, v118
	v_ashrrev_i32_e32 v81, 31, v80
	v_lshlrev_b64 v[80:81], 12, v[80:81]
	v_lshl_add_u64 v[80:81], v[116:117], 0, v[80:81]
	v_lshl_add_u64 v[80:81], v[80:81], 0, v[112:113]
	v_mul_f32_e32 v82, v95, v82
	global_atomic_add_f32 v[80:81], v82, off
	v_mov_b32_e32 v82, v245
	v_mul_f32_e32 v82, v91, v82
	global_atomic_add_f32 v[80:81], v82, off offset:64
	v_mov_b32_e32 v82, v246
	v_mul_f32_e32 v82, v87, v82
	global_atomic_add_f32 v[80:81], v82, off offset:128
	v_mov_b32_e32 v82, v247
	v_mul_f32_e32 v82, v83, v82
	global_atomic_add_f32 v[80:81], v82, off offset:192
	v_mov_b32_e32 v82, v244
	v_add_u32_e32 v80, 32, v118
	v_ashrrev_i32_e32 v81, 31, v80
	v_lshlrev_b64 v[80:81], 12, v[80:81]
	v_lshl_add_u64 v[80:81], v[116:117], 0, v[80:81]
	v_lshl_add_u64 v[80:81], v[80:81], 0, v[112:113]
	v_mul_f32_e32 v76, v76, v82
	global_atomic_add_f32 v[80:81], v76, off
	v_mov_b32_e32 v76, v245
	v_mul_f32_e32 v72, v72, v76
	global_atomic_add_f32 v[80:81], v72, off offset:64
	v_mov_b32_e32 v72, v246
	v_mul_f32_e32 v68, v68, v72
	global_atomic_add_f32 v[80:81], v68, off offset:128
	v_mov_b32_e32 v68, v247
	v_mul_f32_e32 v64, v64, v68
	global_atomic_add_f32 v[80:81], v64, off offset:192
	v_mov_b32_e32 v64, v244
	v_add_u32_e32 v80, 33, v118
	v_ashrrev_i32_e32 v81, 31, v80
	v_lshlrev_b64 v[80:81], 12, v[80:81]
	v_lshl_add_u64 v[80:81], v[116:117], 0, v[80:81]
	v_lshl_add_u64 v[80:81], v[80:81], 0, v[112:113]
	v_mul_f32_e32 v64, v77, v64
	global_atomic_add_f32 v[80:81], v64, off
	v_mov_b32_e32 v64, v245
	v_mul_f32_e32 v64, v73, v64
	global_atomic_add_f32 v[80:81], v64, off offset:64
	v_mov_b32_e32 v64, v246
	v_mul_f32_e32 v64, v69, v64
	global_atomic_add_f32 v[80:81], v64, off offset:128
	v_mov_b32_e32 v64, v247
	v_mul_f32_e32 v64, v65, v64
	global_atomic_add_f32 v[80:81], v64, off offset:192
	v_mov_b32_e32 v68, v244
	v_add_u32_e32 v64, 34, v118
	v_ashrrev_i32_e32 v65, 31, v64
	v_lshlrev_b64 v[64:65], 12, v[64:65]
	v_lshl_add_u64 v[64:65], v[116:117], 0, v[64:65]
	v_lshl_add_u64 v[64:65], v[64:65], 0, v[112:113]
	v_mul_f32_e32 v68, v78, v68
	global_atomic_add_f32 v[64:65], v68, off
	v_mov_b32_e32 v68, v245
	v_mul_f32_e32 v68, v74, v68
	global_atomic_add_f32 v[64:65], v68, off offset:64
	v_mov_b32_e32 v68, v246
	v_mul_f32_e32 v68, v70, v68
	global_atomic_add_f32 v[64:65], v68, off offset:128
	v_mov_b32_e32 v68, v247
	v_mul_f32_e32 v66, v66, v68
	global_atomic_add_f32 v[64:65], v66, off offset:192
	v_mov_b32_e32 v66, v244
	v_add_u32_e32 v64, 35, v118
	v_ashrrev_i32_e32 v65, 31, v64
	v_lshlrev_b64 v[64:65], 12, v[64:65]
	v_lshl_add_u64 v[64:65], v[116:117], 0, v[64:65]
	v_lshl_add_u64 v[64:65], v[64:65], 0, v[112:113]
	v_mul_f32_e32 v66, v79, v66
	global_atomic_add_f32 v[64:65], v66, off
	v_mov_b32_e32 v66, v245
	v_mul_f32_e32 v66, v75, v66
	global_atomic_add_f32 v[64:65], v66, off offset:64
	v_mov_b32_e32 v66, v246
	v_mul_f32_e32 v66, v71, v66
	global_atomic_add_f32 v[64:65], v66, off offset:128
	v_mov_b32_e32 v66, v247
	v_mul_f32_e32 v66, v67, v66
	global_atomic_add_f32 v[64:65], v66, off offset:192
	v_mov_b32_e32 v66, v244
	v_add_u32_e32 v64, 48, v118
	v_ashrrev_i32_e32 v65, 31, v64
	v_lshlrev_b64 v[64:65], 12, v[64:65]
	v_lshl_add_u64 v[64:65], v[116:117], 0, v[64:65]
	v_lshl_add_u64 v[64:65], v[64:65], 0, v[112:113]
	v_mul_f32_e32 v60, v60, v66
	global_atomic_add_f32 v[64:65], v60, off
	v_mov_b32_e32 v60, v245
	v_mul_f32_e32 v56, v56, v60
	global_atomic_add_f32 v[64:65], v56, off offset:64
	v_mov_b32_e32 v56, v246
	v_mul_f32_e32 v52, v52, v56
	global_atomic_add_f32 v[64:65], v52, off offset:128
	v_mov_b32_e32 v52, v247
	v_mul_f32_e32 v48, v48, v52
	global_atomic_add_f32 v[64:65], v48, off offset:192
	v_mov_b32_e32 v48, v244
	v_add_u32_e32 v64, 49, v118
	v_ashrrev_i32_e32 v65, 31, v64
	v_lshlrev_b64 v[64:65], 12, v[64:65]
	v_lshl_add_u64 v[64:65], v[116:117], 0, v[64:65]
	v_lshl_add_u64 v[64:65], v[64:65], 0, v[112:113]
	v_mul_f32_e32 v48, v61, v48
	global_atomic_add_f32 v[64:65], v48, off
	v_mov_b32_e32 v48, v245
	v_mul_f32_e32 v48, v57, v48
	global_atomic_add_f32 v[64:65], v48, off offset:64
	v_mov_b32_e32 v48, v246
	v_mul_f32_e32 v48, v53, v48
	global_atomic_add_f32 v[64:65], v48, off offset:128
	v_mov_b32_e32 v48, v247
	v_mul_f32_e32 v48, v49, v48
	global_atomic_add_f32 v[64:65], v48, off offset:192
	v_mov_b32_e32 v52, v244
	v_add_u32_e32 v48, 50, v118
	v_ashrrev_i32_e32 v49, 31, v48
	v_lshlrev_b64 v[48:49], 12, v[48:49]
	v_lshl_add_u64 v[48:49], v[116:117], 0, v[48:49]
	v_lshl_add_u64 v[48:49], v[48:49], 0, v[112:113]
	v_mul_f32_e32 v52, v62, v52
	global_atomic_add_f32 v[48:49], v52, off
	v_mov_b32_e32 v52, v245
	v_mul_f32_e32 v52, v58, v52
	global_atomic_add_f32 v[48:49], v52, off offset:64
	v_mov_b32_e32 v52, v246
	v_mul_f32_e32 v52, v54, v52
	global_atomic_add_f32 v[48:49], v52, off offset:128
	v_mov_b32_e32 v52, v247
	v_mul_f32_e32 v50, v50, v52
	global_atomic_add_f32 v[48:49], v50, off offset:192
	v_mov_b32_e32 v50, v244
	v_add_u32_e32 v48, 51, v118
	v_ashrrev_i32_e32 v49, 31, v48
	v_lshlrev_b64 v[48:49], 12, v[48:49]
	v_lshl_add_u64 v[48:49], v[116:117], 0, v[48:49]
	v_lshl_add_u64 v[48:49], v[48:49], 0, v[112:113]
	v_mul_f32_e32 v50, v63, v50
	global_atomic_add_f32 v[48:49], v50, off
	v_mov_b32_e32 v50, v245
	v_mul_f32_e32 v50, v59, v50
	global_atomic_add_f32 v[48:49], v50, off offset:64
	v_mov_b32_e32 v50, v246
	v_mul_f32_e32 v50, v55, v50
	global_atomic_add_f32 v[48:49], v50, off offset:128
	v_mov_b32_e32 v50, v247
	v_mul_f32_e32 v50, v51, v50
	global_atomic_add_f32 v[48:49], v50, off offset:192
	s_branch .LBB0_843

.LBB0_1156:
	s_or_b64 exec, exec, s[78:79]
	s_lshl_b64 s[72:73], s[76:77], 24
	v_readlane_b32 s8, v251, 38
	v_lshl_add_u64 v[4:5], v[36:37], 0, v[4:5]
	v_readlane_b32 s9, v251, 39
	s_add_u32 s72, s8, s72
	v_lshlrev_b64 v[4:5], 11, v[4:5]
	s_addc_u32 s73, s9, s73
	v_lshl_add_u64 v[4:5], s[72:73], 0, v[4:5]
	v_lshl_add_u64 v[2:3], v[2:3], 1, v[4:5]
	v_mov_b32_e32 v55, v1
	v_lshl_add_u64 v[2:3], v[2:3], 0, v[54:55]
	s_waitcnt vmcnt(0)
	v_mul_f32_e32 v0, 0x3fb8aa3b, v6
	s_waitcnt lgkmcnt(0)
	s_barrier
	global_load_dwordx4 v[4:7], v[2:3], off
	global_load_dwordx4 v[92:95], v[2:3], off offset:64
	global_load_dwordx4 v[96:99], v[2:3], off offset:128
	global_load_dwordx4 v[100:103], v[2:3], off offset:192
	global_load_dwordx4 v[104:107], v[2:3], off offset:256
	global_load_dwordx4 v[108:111], v[2:3], off offset:320
	global_load_dwordx4 v[112:115], v[2:3], off offset:384
	global_load_dwordx4 v[116:119], v[2:3], off offset:448
	ds_read_b128 v[8:11], v68
	ds_read_b128 v[78:81], v68 offset:64
	ds_read_b128 v[12:15], v68 offset:8448
	ds_read_b128 v[16:19], v68 offset:16896
	ds_read_b128 v[20:23], v68 offset:25344
	ds_read_b128 v[24:27], v68 offset:33792
	ds_read_b128 v[28:31], v68 offset:42240
	ds_read_b128 v[70:73], v68 offset:50688
	ds_read_b128 v[74:77], v68 offset:59136
	s_lshl_b64 s[70:71], s[70:71], 21
	v_readlane_b32 s8, v252, 26
	v_readlane_b32 s9, v252, 27
	s_add_u32 s70, s8, s70
	v_exp_f32_e32 v0, v0
	s_addc_u32 s71, s9, s71
	s_lshl_b32 s72, s90, 15
	s_add_u32 s76, s70, s72
	s_addc_u32 s77, s71, 0
	s_cmpk_lt_u32 s89, 0x100
	s_cselect_b64 s[70:71], -1, 0
	v_mul_f32_e32 v55, v0, v60
	v_mul_f32_e64 v56, -v0, v61
	v_readlane_b32 s8, v251, 18
	v_cndmask_b32_e64 v55, v55, v56, s[70:71]
	v_readlane_b32 s9, v251, 19
	v_mul_f32_e32 v55, 0x3fb8aa3b, v55
	v_exp_f32_e32 v55, v55
	v_cndmask_b32_e64 v56, 0, 1, s[8:9]
	v_readlane_b32 s8, v251, 0
	v_readlane_b32 s9, v251, 1
	s_waitcnt vmcnt(7) lgkmcnt(8)
	v_mfma_f32_16x16x32_bf16 v[8:11], v[4:7], v[8:11], 0
	v_cndmask_b32_e64 v57, 0, 1, s[8:9]
	v_cndmask_b32_e64 v56, v57, v56, s[70:71]
	v_and_b32_e32 v56, 1, v56
	s_waitcnt lgkmcnt(6)
	v_mfma_f32_16x16x32_bf16 v[12:15], v[4:7], v[12:15], 0
	v_cmp_eq_u32_e32 vcc, 1, v56
	v_readlane_b32 s8, v251, 58
	v_readlane_b32 s9, v251, 59
	s_waitcnt lgkmcnt(5)
	v_mfma_f32_16x16x32_bf16 v[16:19], v[4:7], v[16:19], 0
	s_waitcnt lgkmcnt(4)
	v_mfma_f32_16x16x32_bf16 v[20:23], v[4:7], v[20:23], 0
	s_waitcnt lgkmcnt(3)
	v_mfma_f32_16x16x32_bf16 v[24:27], v[4:7], v[24:27], 0
	s_waitcnt lgkmcnt(2)
	v_mfma_f32_16x16x32_bf16 v[28:31], v[4:7], v[28:31], 0
	s_waitcnt lgkmcnt(1)
	v_mfma_f32_16x16x32_bf16 v[70:73], v[4:7], v[70:73], 0
	s_waitcnt lgkmcnt(0)
	v_mfma_f32_16x16x32_bf16 v[4:7], v[4:7], v[74:77], 0
	ds_read_b128 v[156:159], v68 offset:64
	ds_read_b128 v[172:175], v68 offset:8512
	ds_read_b128 v[176:179], v68 offset:16960
	ds_read_b128 v[180:183], v68 offset:25408
	ds_read_b128 v[184:187], v68 offset:33856
	ds_read_b128 v[188:191], v68 offset:42304
	ds_read_b128 v[192:195], v68 offset:50752
	ds_read_b128 v[196:199], v68 offset:59200
	s_waitcnt vmcnt(6)
	s_waitcnt lgkmcnt(7)
	v_mfma_f32_16x16x32_bf16 v[8:11], v[92:95], v[156:159], v[8:11]
	ds_read_b128 v[124:127], v68 offset:128
	ds_read_b128 v[128:131], v68 offset:8576
	ds_read_b128 v[132:135], v68 offset:17024
	ds_read_b128 v[136:139], v68 offset:25472
	ds_read_b128 v[140:143], v68 offset:33920
	ds_read_b128 v[144:147], v68 offset:42368
	ds_read_b128 v[148:151], v68 offset:50816
	ds_read_b128 v[152:155], v68 offset:59264
	s_waitcnt lgkmcnt(14)
	v_mfma_f32_16x16x32_bf16 v[12:15], v[92:95], v[172:175], v[12:15]
	s_waitcnt lgkmcnt(13)
	v_mfma_f32_16x16x32_bf16 v[16:19], v[92:95], v[176:179], v[16:19]
	s_waitcnt lgkmcnt(12)
	v_mfma_f32_16x16x32_bf16 v[20:23], v[92:95], v[180:183], v[20:23]
	s_waitcnt lgkmcnt(11)
	v_mfma_f32_16x16x32_bf16 v[24:27], v[92:95], v[184:187], v[24:27]
	s_waitcnt lgkmcnt(10)
	v_mfma_f32_16x16x32_bf16 v[28:31], v[92:95], v[188:191], v[28:31]
	s_waitcnt lgkmcnt(9)
	v_mfma_f32_16x16x32_bf16 v[70:73], v[92:95], v[192:195], v[70:73]
	s_waitcnt lgkmcnt(8)
	v_mfma_f32_16x16x32_bf16 v[4:7], v[92:95], v[196:199], v[4:7]
	s_waitcnt vmcnt(5)
	s_waitcnt lgkmcnt(7)
	v_mfma_f32_16x16x32_bf16 v[8:11], v[96:99], v[124:127], v[8:11]
	ds_read_b128 v[156:159], v68 offset:192
	ds_read_b128 v[172:175], v68 offset:8640
	ds_read_b128 v[176:179], v68 offset:17088
	ds_read_b128 v[180:183], v68 offset:25536
	ds_read_b128 v[184:187], v68 offset:33984
	ds_read_b128 v[188:191], v68 offset:42432
	ds_read_b128 v[192:195], v68 offset:50880
	ds_read_b128 v[196:199], v68 offset:59328
	s_waitcnt lgkmcnt(14)
	v_mfma_f32_16x16x32_bf16 v[12:15], v[96:99], v[128:131], v[12:15]
	s_waitcnt lgkmcnt(13)
	v_mfma_f32_16x16x32_bf16 v[16:19], v[96:99], v[132:135], v[16:19]
	s_waitcnt lgkmcnt(12)
	v_mfma_f32_16x16x32_bf16 v[20:23], v[96:99], v[136:139], v[20:23]
	s_waitcnt lgkmcnt(11)
	v_mfma_f32_16x16x32_bf16 v[24:27], v[96:99], v[140:143], v[24:27]
	s_waitcnt lgkmcnt(10)
	v_mfma_f32_16x16x32_bf16 v[28:31], v[96:99], v[144:147], v[28:31]
	s_waitcnt lgkmcnt(9)
	v_mfma_f32_16x16x32_bf16 v[70:73], v[96:99], v[148:151], v[70:73]
	s_waitcnt lgkmcnt(8)
	v_mfma_f32_16x16x32_bf16 v[4:7], v[96:99], v[152:155], v[4:7]
	s_waitcnt vmcnt(4)
	s_waitcnt lgkmcnt(7)
	v_mfma_f32_16x16x32_bf16 v[8:11], v[100:103], v[156:159], v[8:11]
	ds_read_b128 v[124:127], v68 offset:256
	ds_read_b128 v[128:131], v68 offset:8704
	ds_read_b128 v[132:135], v68 offset:17152
	ds_read_b128 v[136:139], v68 offset:25600
	ds_read_b128 v[140:143], v68 offset:34048
	ds_read_b128 v[144:147], v68 offset:42496
	ds_read_b128 v[148:151], v68 offset:50944
	ds_read_b128 v[152:155], v68 offset:59392
	s_waitcnt lgkmcnt(14)
	v_mfma_f32_16x16x32_bf16 v[12:15], v[100:103], v[172:175], v[12:15]
	s_waitcnt lgkmcnt(13)
	v_mfma_f32_16x16x32_bf16 v[16:19], v[100:103], v[176:179], v[16:19]
	s_waitcnt lgkmcnt(12)
	v_mfma_f32_16x16x32_bf16 v[20:23], v[100:103], v[180:183], v[20:23]
	s_waitcnt lgkmcnt(11)
	v_mfma_f32_16x16x32_bf16 v[24:27], v[100:103], v[184:187], v[24:27]
	s_waitcnt lgkmcnt(10)
	v_mfma_f32_16x16x32_bf16 v[28:31], v[100:103], v[188:191], v[28:31]
	s_waitcnt lgkmcnt(9)
	v_mfma_f32_16x16x32_bf16 v[70:73], v[100:103], v[192:195], v[70:73]
	s_waitcnt lgkmcnt(8)
	v_mfma_f32_16x16x32_bf16 v[4:7], v[100:103], v[196:199], v[4:7]
	s_waitcnt vmcnt(3)
	s_waitcnt lgkmcnt(7)
	v_mfma_f32_16x16x32_bf16 v[8:11], v[104:107], v[124:127], v[8:11]
	ds_read_b128 v[156:159], v68 offset:320
	ds_read_b128 v[172:175], v68 offset:8768
	ds_read_b128 v[176:179], v68 offset:17216
	ds_read_b128 v[180:183], v68 offset:25664
	ds_read_b128 v[184:187], v68 offset:34112
	ds_read_b128 v[188:191], v68 offset:42560
	ds_read_b128 v[192:195], v68 offset:51008
	ds_read_b128 v[196:199], v68 offset:59456
	s_waitcnt lgkmcnt(14)
	v_mfma_f32_16x16x32_bf16 v[12:15], v[104:107], v[128:131], v[12:15]
	s_waitcnt lgkmcnt(13)
	v_mfma_f32_16x16x32_bf16 v[16:19], v[104:107], v[132:135], v[16:19]
	s_waitcnt lgkmcnt(12)
	v_mfma_f32_16x16x32_bf16 v[20:23], v[104:107], v[136:139], v[20:23]
	s_waitcnt lgkmcnt(11)
	v_mfma_f32_16x16x32_bf16 v[24:27], v[104:107], v[140:143], v[24:27]
	s_waitcnt lgkmcnt(10)
	v_mfma_f32_16x16x32_bf16 v[28:31], v[104:107], v[144:147], v[28:31]
	s_waitcnt lgkmcnt(9)
	v_mfma_f32_16x16x32_bf16 v[70:73], v[104:107], v[148:151], v[70:73]
	s_waitcnt lgkmcnt(8)
	v_mfma_f32_16x16x32_bf16 v[4:7], v[104:107], v[152:155], v[4:7]
	s_waitcnt vmcnt(2)
	s_waitcnt lgkmcnt(7)
	v_mfma_f32_16x16x32_bf16 v[8:11], v[108:111], v[156:159], v[8:11]
	s_waitcnt lgkmcnt(6)
	v_mfma_f32_16x16x32_bf16 v[12:15], v[108:111], v[172:175], v[12:15]
	s_waitcnt lgkmcnt(5)
	v_mfma_f32_16x16x32_bf16 v[16:19], v[108:111], v[176:179], v[16:19]
	s_waitcnt lgkmcnt(4)
	v_mfma_f32_16x16x32_bf16 v[20:23], v[108:111], v[180:183], v[20:23]
	s_waitcnt lgkmcnt(3)
	v_mfma_f32_16x16x32_bf16 v[24:27], v[108:111], v[184:187], v[24:27]
	s_waitcnt lgkmcnt(2)
	v_mfma_f32_16x16x32_bf16 v[28:31], v[108:111], v[188:191], v[28:31]
	s_waitcnt lgkmcnt(1)
	v_mfma_f32_16x16x32_bf16 v[70:73], v[108:111], v[192:195], v[70:73]
	s_waitcnt lgkmcnt(0)
	v_mfma_f32_16x16x32_bf16 v[4:7], v[108:111], v[196:199], v[4:7]
	ds_read_b128 v[78:81], v68 offset:384
	s_waitcnt vmcnt(1) lgkmcnt(0)
	v_mfma_f32_16x16x32_bf16 v[8:11], v[112:115], v[78:81], v[8:11]
	ds_read_b128 v[78:81], v68 offset:8832
	s_waitcnt lgkmcnt(0)
	v_mfma_f32_16x16x32_bf16 v[12:15], v[112:115], v[78:81], v[12:15]
	ds_read_b128 v[78:81], v68 offset:17280
	s_waitcnt lgkmcnt(0)
	v_mfma_f32_16x16x32_bf16 v[16:19], v[112:115], v[78:81], v[16:19]
	ds_read_b128 v[78:81], v68 offset:25728
	s_waitcnt lgkmcnt(0)
	v_mfma_f32_16x16x32_bf16 v[78:81], v[112:115], v[78:81], v[20:23]
	s_nop 2
	ds_read_b128 v[20:23], v68 offset:34176
	s_waitcnt lgkmcnt(0)
	v_mfma_f32_16x16x32_bf16 v[82:85], v[112:115], v[20:23], v[24:27]
	ds_read_b128 v[20:23], v68 offset:42624
	s_waitcnt lgkmcnt(0)
	v_mfma_f32_16x16x32_bf16 v[86:89], v[112:115], v[20:23], v[28:31]
	ds_read_b128 v[20:23], v68 offset:51072
	s_waitcnt lgkmcnt(0)
	v_mfma_f32_16x16x32_bf16 v[70:73], v[112:115], v[20:23], v[70:73]
	ds_read_b128 v[20:23], v68 offset:59520
	s_waitcnt lgkmcnt(0)
	v_mfma_f32_16x16x32_bf16 v[74:77], v[112:115], v[20:23], v[4:7]
	ds_read_b128 v[20:23], v68 offset:448
	s_nop 1
	s_waitcnt vmcnt(0) lgkmcnt(0)
	v_mfma_f32_16x16x32_bf16 v[30:33], v[116:119], v[20:23], v[8:11]
	s_nop 2
	ds_read_b128 v[6:9], v68 offset:8896
	s_nop 3
	v_mul_f32_e32 v30, v55, v30
	v_cndmask_b32_e32 v30, 0, v30, vcc
	v_bfe_u32 v56, v30, 16, 1
	v_add3_u32 v30, v30, v56, s33
	v_lshl_add_u64 v[56:57], v[38:39], 1, s[76:77]
	global_store_short_d16_hi v[56:57], v30, off
	v_cndmask_b32_e64 v30, 0, 1, s[8:9]
	v_readlane_b32 s8, v252, 0
	s_waitcnt lgkmcnt(0)
	v_mfma_f32_16x16x32_bf16 v[26:29], v[116:119], v[6:9], v[12:15]
	v_readlane_b32 s9, v252, 1
	ds_read_b128 v[6:9], v68 offset:17344
	s_nop 0
	v_cndmask_b32_e64 v56, 0, 1, s[8:9]
	v_cndmask_b32_e64 v30, v56, v30, s[70:71]
	v_and_b32_e32 v30, 1, v30
	v_cmp_eq_u32_e32 vcc, 1, v30
	s_nop 0
	v_mul_f32_e32 v26, v55, v26
	v_readlane_b32 s8, v254, 17
	v_cndmask_b32_e32 v26, 0, v26, vcc
	v_bfe_u32 v30, v26, 16, 1
	v_add3_u32 v26, v26, v30, s33
	v_lshl_add_u64 v[56:57], v[46:47], 1, s[76:77]
	v_readlane_b32 s9, v254, 18
	global_store_short_d16_hi v[56:57], v26, off offset:512
	s_waitcnt lgkmcnt(0)
	v_mfma_f32_16x16x32_bf16 v[22:25], v[116:119], v[6:9], v[16:19]
	v_cndmask_b32_e64 v26, 0, 1, s[8:9]
	v_readlane_b32 s8, v254, 19
	v_readlane_b32 s9, v254, 20
	ds_read_b128 v[6:9], v68 offset:25792
	s_waitcnt lgkmcnt(0)
	v_mfma_f32_16x16x32_bf16 v[18:21], v[116:119], v[6:9], v[78:81]
	v_cndmask_b32_e64 v30, 0, 1, s[8:9]
	v_cndmask_b32_e64 v26, v30, v26, s[70:71]
	v_and_b32_e32 v26, 1, v26
	v_cmp_eq_u32_e32 vcc, 1, v26
	v_mul_f32_e32 v22, v55, v22
	v_readlane_b32 s8, v254, 21
	v_cndmask_b32_e32 v22, 0, v22, vcc
	v_bfe_u32 v26, v22, 16, 1
	v_add3_u32 v22, v22, v26, s33
	v_readlane_b32 s9, v254, 22
	global_store_short_d16_hi v[56:57], v22, off offset:1024
	ds_read_b128 v[6:9], v68 offset:34240
	v_cndmask_b32_e64 v22, 0, 1, s[8:9]
	v_readlane_b32 s8, v254, 23
	v_readlane_b32 s9, v254, 24
	v_mul_f32_e32 v18, v55, v18
	s_waitcnt lgkmcnt(0)
	v_mfma_f32_16x16x32_bf16 v[14:17], v[116:119], v[6:9], v[82:85]
	v_cndmask_b32_e64 v26, 0, 1, s[8:9]
	v_cndmask_b32_e64 v22, v26, v22, s[70:71]
	v_and_b32_e32 v22, 1, v22
	v_cmp_eq_u32_e32 vcc, 1, v22
	v_readlane_b32 s8, v254, 25
	v_readlane_b32 s9, v254, 26
	v_cndmask_b32_e32 v18, 0, v18, vcc
	v_bfe_u32 v22, v18, 16, 1
	v_add3_u32 v18, v18, v22, s33
	global_store_short_d16_hi v[56:57], v18, off offset:1536
	v_cndmask_b32_e64 v18, 0, 1, s[8:9]
	v_readlane_b32 s8, v254, 27
	v_readlane_b32 s9, v254, 28
	ds_read_b128 v[6:9], v68 offset:42688
	v_mul_f32_e32 v14, v55, v14
	v_cndmask_b32_e64 v22, 0, 1, s[8:9]
	v_cndmask_b32_e64 v18, v22, v18, s[70:71]
	v_and_b32_e32 v18, 1, v18
	v_cmp_eq_u32_e32 vcc, 1, v18
	v_readlane_b32 s8, v254, 29
	v_readlane_b32 s9, v254, 30
	v_cndmask_b32_e32 v14, 0, v14, vcc
	v_bfe_u32 v18, v14, 16, 1
	v_add3_u32 v14, v14, v18, s33
	global_store_short_d16_hi v[56:57], v14, off offset:2048
	v_cndmask_b32_e64 v14, 0, 1, s[8:9]
	v_readlane_b32 s8, v254, 31
	s_waitcnt lgkmcnt(0)
	v_mfma_f32_16x16x32_bf16 v[10:13], v[116:119], v[6:9], v[86:89]
	v_readlane_b32 s9, v254, 32
	ds_read_b128 v[6:9], v68 offset:51136
	s_nop 0
	v_cndmask_b32_e64 v18, 0, 1, s[8:9]
	v_cndmask_b32_e64 v14, v18, v14, s[70:71]
	v_and_b32_e32 v14, 1, v14
	v_cmp_eq_u32_e32 vcc, 1, v14
	s_nop 0
	v_mul_f32_e32 v10, v55, v10
	v_readlane_b32 s8, v254, 33
	v_cndmask_b32_e32 v10, 0, v10, vcc
	v_bfe_u32 v14, v10, 16, 1
	v_add3_u32 v10, v10, v14, s33
	v_readlane_b32 s9, v254, 34
	global_store_short_d16_hi v[56:57], v10, off offset:2560
	s_waitcnt lgkmcnt(0)
	v_mfma_f32_16x16x32_bf16 v[6:9], v[116:119], v[6:9], v[70:73]
	v_cndmask_b32_e64 v10, 0, 1, s[8:9]
	v_readlane_b32 s8, v254, 35
	v_readlane_b32 s9, v254, 36
	ds_read_b128 v[70:73], v68 offset:59584
	s_waitcnt lgkmcnt(0)
	v_mfma_f32_16x16x32_bf16 v[2:5], v[116:119], v[70:73], v[74:77]
	v_cndmask_b32_e64 v14, 0, 1, s[8:9]
	v_cndmask_b32_e64 v10, v14, v10, s[70:71]
	v_and_b32_e32 v10, 1, v10
	v_cmp_eq_u32_e32 vcc, 1, v10
	v_mul_f32_e32 v6, v55, v6
	v_readlane_b32 s8, v254, 37
	v_cndmask_b32_e32 v6, 0, v6, vcc
	v_bfe_u32 v10, v6, 16, 1
	v_add3_u32 v6, v6, v10, s33
	v_readlane_b32 s9, v254, 38
	global_store_short_d16_hi v[56:57], v6, off offset:3072
	v_mul_f32_e32 v2, v55, v2
	v_cndmask_b32_e64 v6, 0, 1, s[8:9]
	v_readlane_b32 s8, v254, 39
	v_readlane_b32 s9, v254, 40
	s_nop 1
	v_cndmask_b32_e64 v10, 0, 1, s[8:9]
	v_cndmask_b32_e64 v6, v10, v6, s[70:71]
	v_and_b32_e32 v6, 1, v6
	v_cmp_eq_u32_e32 vcc, 1, v6
	v_readlane_b32 s8, v254, 41
	v_readlane_b32 s9, v254, 42
	v_cndmask_b32_e32 v2, 0, v2, vcc
	v_bfe_u32 v6, v2, 16, 1
	v_add3_u32 v2, v2, v6, s33
	global_store_short_d16_hi v[56:57], v2, off offset:3584
	v_mul_f32_e64 v2, -v0, v63
	v_mul_f32_e32 v6, v0, v62
	v_cndmask_b32_e64 v2, v6, v2, s[70:71]
	v_mul_f32_e32 v2, 0x3fb8aa3b, v2
	v_cndmask_b32_e64 v6, 0, 1, s[8:9]
	v_readlane_b32 s8, v254, 43
	v_exp_f32_e32 v2, v2
	v_readlane_b32 s9, v254, 44
	s_nop 1
	v_cndmask_b32_e64 v10, 0, 1, s[8:9]
	v_cndmask_b32_e64 v6, v10, v6, s[70:71]
	v_and_b32_e32 v6, 1, v6
	v_cmp_eq_u32_e32 vcc, 1, v6
	v_mul_f32_e32 v6, v2, v31
	v_readlane_b32 s8, v254, 45
	v_cndmask_b32_e32 v6, 0, v6, vcc
	v_bfe_u32 v10, v6, 16, 1
	v_add3_u32 v6, v6, v10, s33
	v_lshl_add_u64 v[30:31], v[40:41], 1, s[76:77]
	v_readlane_b32 s9, v254, 46
	global_store_short_d16_hi v[30:31], v6, off
	s_nop 0
	v_cndmask_b32_e64 v6, 0, 1, s[8:9]
	v_readlane_b32 s8, v254, 47
	v_readlane_b32 s9, v254, 48
	s_nop 1
	v_cndmask_b32_e64 v10, 0, 1, s[8:9]
	v_cndmask_b32_e64 v6, v10, v6, s[70:71]
	v_and_b32_e32 v6, 1, v6
	v_cmp_eq_u32_e32 vcc, 1, v6
	v_mul_f32_e32 v6, v2, v27
	v_readlane_b32 s8, v254, 49
	v_cndmask_b32_e32 v6, 0, v6, vcc
	v_bfe_u32 v10, v6, 16, 1
	v_add3_u32 v6, v6, v10, s33
	v_lshl_add_u64 v[26:27], v[48:49], 1, s[76:77]
	v_readlane_b32 s9, v254, 50
	global_store_short_d16_hi v[26:27], v6, off offset:512
	s_nop 0
	v_cndmask_b32_e64 v6, 0, 1, s[8:9]
	v_readlane_b32 s8, v254, 51
	v_readlane_b32 s9, v254, 52
	s_nop 1
	v_cndmask_b32_e64 v10, 0, 1, s[8:9]
	v_cndmask_b32_e64 v6, v10, v6, s[70:71]
	v_and_b32_e32 v6, 1, v6
	v_cmp_eq_u32_e32 vcc, 1, v6
	v_mul_f32_e32 v6, v2, v23
	v_readlane_b32 s8, v254, 53
	v_cndmask_b32_e32 v6, 0, v6, vcc
	v_bfe_u32 v10, v6, 16, 1
	v_add3_u32 v6, v6, v10, s33
	v_readlane_b32 s9, v254, 54
	global_store_short_d16_hi v[26:27], v6, off offset:1024
	s_nop 0
	v_cndmask_b32_e64 v6, 0, 1, s[8:9]
	v_readlane_b32 s8, v254, 55
	v_readlane_b32 s9, v254, 56
	s_nop 1
	v_cndmask_b32_e64 v10, 0, 1, s[8:9]
	v_cndmask_b32_e64 v6, v10, v6, s[70:71]
	v_and_b32_e32 v6, 1, v6
	v_cmp_eq_u32_e32 vcc, 1, v6
	v_mul_f32_e32 v6, v2, v19
	v_readlane_b32 s8, v254, 57
	v_cndmask_b32_e32 v6, 0, v6, vcc
	v_bfe_u32 v10, v6, 16, 1
	v_add3_u32 v6, v6, v10, s33
	v_readlane_b32 s9, v254, 58
	global_store_short_d16_hi v[26:27], v6, off offset:1536
	s_nop 0
	v_cndmask_b32_e64 v6, 0, 1, s[8:9]
	v_readlane_b32 s8, v254, 59
	v_readlane_b32 s9, v254, 60
	s_nop 1
	v_cndmask_b32_e64 v10, 0, 1, s[8:9]
	v_cndmask_b32_e64 v6, v10, v6, s[70:71]
	v_and_b32_e32 v6, 1, v6
	v_cmp_eq_u32_e32 vcc, 1, v6
	v_mul_f32_e32 v6, v2, v15
	v_readlane_b32 s8, v254, 61
	v_cndmask_b32_e32 v6, 0, v6, vcc
	v_bfe_u32 v10, v6, 16, 1
	v_add3_u32 v6, v6, v10, s33
	v_readlane_b32 s9, v254, 62
	global_store_short_d16_hi v[26:27], v6, off offset:2048
	s_nop 0
	v_cndmask_b32_e64 v6, 0, 1, s[8:9]
	v_readlane_b32 s8, v254, 63
	v_readlane_b32 s9, v255, 0
	s_nop 1
	v_cndmask_b32_e64 v10, 0, 1, s[8:9]
	v_cndmask_b32_e64 v6, v10, v6, s[70:71]
	v_and_b32_e32 v6, 1, v6
	v_cmp_eq_u32_e32 vcc, 1, v6
	v_mul_f32_e32 v6, v2, v11
	v_readlane_b32 s8, v255, 1
	v_cndmask_b32_e32 v6, 0, v6, vcc
	v_bfe_u32 v10, v6, 16, 1
	v_add3_u32 v6, v6, v10, s33
	v_readlane_b32 s9, v255, 2
	global_store_short_d16_hi v[26:27], v6, off offset:2560
	s_nop 0
	v_cndmask_b32_e64 v6, 0, 1, s[8:9]
	v_readlane_b32 s8, v255, 3
	v_readlane_b32 s9, v255, 4
	s_nop 1
	v_cndmask_b32_e64 v10, 0, 1, s[8:9]
	v_cndmask_b32_e64 v6, v10, v6, s[70:71]
	v_and_b32_e32 v6, 1, v6
	v_cmp_eq_u32_e32 vcc, 1, v6
	v_mul_f32_e32 v6, v2, v7
	v_readlane_b32 s8, v255, 5
	v_cndmask_b32_e32 v6, 0, v6, vcc
	v_bfe_u32 v7, v6, 16, 1
	v_add3_u32 v6, v6, v7, s33
	v_readlane_b32 s9, v255, 6
	global_store_short_d16_hi v[26:27], v6, off offset:3072
	v_cndmask_b32_e64 v7, 0, 1, s[92:93]
	v_cndmask_b32_e64 v6, 0, 1, s[8:9]
	v_cndmask_b32_e64 v6, v7, v6, s[70:71]
	v_and_b32_e32 v6, 1, v6
	v_cmp_eq_u32_e32 vcc, 1, v6
	v_mul_f32_e32 v2, v2, v3
	v_cndmask_b32_e64 v10, 0, 1, s[20:21]
	v_cndmask_b32_e32 v2, 0, v2, vcc
	v_bfe_u32 v3, v2, 16, 1
	v_add3_u32 v2, v2, v3, s33
	global_store_short_d16_hi v[26:27], v2, off offset:3584
	v_mul_f32_e64 v2, -v0, v65
	v_mul_f32_e32 v3, v0, v64
	v_cndmask_b32_e64 v2, v3, v2, s[70:71]
	v_mul_f32_e32 v2, 0x3fb8aa3b, v2
	v_exp_f32_e32 v6, v2
	v_cndmask_b32_e64 v2, 0, 1, s[94:95]
	v_cndmask_b32_e64 v3, 0, 1, s[96:97]
	v_cndmask_b32_e64 v2, v3, v2, s[70:71]
	v_and_b32_e32 v2, 1, v2
	v_cmp_eq_u32_e32 vcc, 1, v2
	v_mul_f32_e32 v2, v6, v32
	v_mul_f32_e32 v4, v6, v4
	v_cndmask_b32_e32 v2, 0, v2, vcc
	v_bfe_u32 v3, v2, 16, 1
	v_add3_u32 v7, v2, v3, s33
	v_lshl_add_u64 v[2:3], v[42:43], 1, s[76:77]
	global_store_short_d16_hi v[2:3], v7, off
	v_cndmask_b32_e64 v2, 0, 1, s[6:7]
	v_cndmask_b32_e64 v3, 0, 1, s[16:17]
	v_cndmask_b32_e64 v2, v3, v2, s[70:71]
	v_and_b32_e32 v2, 1, v2
	v_cmp_eq_u32_e32 vcc, 1, v2
	v_mul_f32_e32 v2, v6, v28
	s_nop 0
	v_cndmask_b32_e32 v2, 0, v2, vcc
	v_bfe_u32 v3, v2, 16, 1
	v_add3_u32 v7, v2, v3, s33
	v_lshl_add_u64 v[2:3], v[50:51], 1, s[76:77]
	global_store_short_d16_hi v[2:3], v7, off offset:512
	v_cndmask_b32_e64 v7, 0, 1, s[18:19]
	v_cndmask_b32_e64 v7, v10, v7, s[70:71]
	v_and_b32_e32 v7, 1, v7
	v_cmp_eq_u32_e32 vcc, 1, v7
	v_mul_f32_e32 v7, v6, v24
	s_nop 0
	v_cndmask_b32_e32 v7, 0, v7, vcc
	v_bfe_u32 v10, v7, 16, 1
	v_add3_u32 v7, v7, v10, s33
	global_store_short_d16_hi v[2:3], v7, off offset:1024
	v_cndmask_b32_e64 v7, 0, 1, s[22:23]
	v_cndmask_b32_e64 v10, 0, 1, s[24:25]
	v_cndmask_b32_e64 v7, v10, v7, s[70:71]
	v_and_b32_e32 v7, 1, v7
	v_cmp_eq_u32_e32 vcc, 1, v7
	v_mul_f32_e32 v7, v6, v20
	s_nop 0
	v_cndmask_b32_e32 v7, 0, v7, vcc
	v_bfe_u32 v10, v7, 16, 1
	v_add3_u32 v7, v7, v10, s33
	global_store_short_d16_hi v[2:3], v7, off offset:1536
	v_cndmask_b32_e64 v7, 0, 1, s[26:27]
	v_cndmask_b32_e64 v10, 0, 1, s[28:29]
	v_cndmask_b32_e64 v7, v10, v7, s[70:71]
	v_and_b32_e32 v7, 1, v7
	v_cmp_eq_u32_e32 vcc, 1, v7
	v_mul_f32_e32 v7, v6, v16
	s_nop 0
	v_cndmask_b32_e32 v7, 0, v7, vcc
	v_bfe_u32 v10, v7, 16, 1
	v_add3_u32 v7, v7, v10, s33
	global_store_short_d16_hi v[2:3], v7, off offset:2048
	v_cndmask_b32_e64 v7, 0, 1, s[30:31]
	v_cndmask_b32_e64 v10, 0, 1, s[34:35]
	v_cndmask_b32_e64 v7, v10, v7, s[70:71]
	v_and_b32_e32 v7, 1, v7
	v_cmp_eq_u32_e32 vcc, 1, v7
	v_mul_f32_e32 v7, v6, v12
	s_nop 0
	v_cndmask_b32_e32 v7, 0, v7, vcc
	v_bfe_u32 v10, v7, 16, 1
	v_add3_u32 v7, v7, v10, s33
	global_store_short_d16_hi v[2:3], v7, off offset:2560
	v_cndmask_b32_e64 v7, 0, 1, s[36:37]
	v_cndmask_b32_e64 v10, 0, 1, s[0:1]
	v_cndmask_b32_e64 v7, v10, v7, s[70:71]
	v_and_b32_e32 v7, 1, v7
	v_cmp_eq_u32_e32 vcc, 1, v7
	v_mul_f32_e32 v7, v6, v8
	s_nop 0
	v_cndmask_b32_e32 v7, 0, v7, vcc
	v_bfe_u32 v8, v7, 16, 1
	v_add3_u32 v7, v7, v8, s33
	global_store_short_d16_hi v[2:3], v7, off offset:3072
	v_cndmask_b32_e64 v7, 0, 1, s[2:3]
	v_cndmask_b32_e64 v8, 0, 1, s[4:5]
	v_cndmask_b32_e64 v7, v8, v7, s[70:71]
	v_and_b32_e32 v7, 1, v7
	v_cmp_eq_u32_e32 vcc, 1, v7
	s_nop 1
	v_cndmask_b32_e32 v4, 0, v4, vcc
	v_bfe_u32 v6, v4, 16, 1
	v_add3_u32 v4, v4, v6, s33
	global_store_short_d16_hi v[2:3], v4, off offset:3584
	v_mul_f32_e64 v2, -v0, v67
	v_mul_f32_e32 v0, v0, v66
	v_cndmask_b32_e64 v0, v0, v2, s[70:71]
	v_mul_f32_e32 v0, 0x3fb8aa3b, v0
	v_exp_f32_e32 v0, v0
	v_cndmask_b32_e64 v2, 0, 1, s[38:39]
	v_cndmask_b32_e64 v3, 0, 1, s[40:41]
	v_cndmask_b32_e64 v2, v3, v2, s[70:71]
	v_and_b32_e32 v2, 1, v2
	v_cmp_eq_u32_e32 vcc, 1, v2
	v_mul_f32_e32 v2, v0, v33
	v_cndmask_b32_e64 v6, 0, 1, s[48:49]
	v_cndmask_b32_e32 v2, 0, v2, vcc
	v_bfe_u32 v3, v2, 16, 1
	v_add3_u32 v4, v2, v3, s33
	v_lshl_add_u64 v[2:3], v[44:45], 1, s[76:77]
	global_store_short_d16_hi v[2:3], v4, off
	v_cndmask_b32_e64 v2, 0, 1, s[42:43]
	v_cndmask_b32_e64 v3, 0, 1, s[44:45]
	v_cndmask_b32_e64 v2, v3, v2, s[70:71]
	v_and_b32_e32 v2, 1, v2
	v_cmp_eq_u32_e32 vcc, 1, v2
	v_mul_f32_e32 v2, v0, v29
	s_nop 0
	v_cndmask_b32_e32 v2, 0, v2, vcc
	v_bfe_u32 v3, v2, 16, 1
	v_add3_u32 v4, v2, v3, s33
	v_lshl_add_u64 v[2:3], v[52:53], 1, s[76:77]
	global_store_short_d16_hi v[2:3], v4, off offset:512
	v_cndmask_b32_e64 v4, 0, 1, s[46:47]
	v_cndmask_b32_e64 v4, v6, v4, s[70:71]
	v_and_b32_e32 v4, 1, v4
	v_cmp_eq_u32_e32 vcc, 1, v4
	v_mul_f32_e32 v4, v0, v25
	v_readlane_b32 s76, v252, 17
	v_cndmask_b32_e32 v4, 0, v4, vcc
	v_bfe_u32 v6, v4, 16, 1
	v_add3_u32 v4, v4, v6, s33
	global_store_short_d16_hi v[2:3], v4, off offset:1024
	v_cndmask_b32_e64 v4, 0, 1, s[50:51]
	v_cndmask_b32_e64 v6, 0, 1, s[52:53]
	v_cndmask_b32_e64 v4, v6, v4, s[70:71]
	v_and_b32_e32 v4, 1, v4
	v_cmp_eq_u32_e32 vcc, 1, v4
	v_mul_f32_e32 v4, v0, v21
	v_readlane_b32 s78, v252, 19
	v_cndmask_b32_e32 v4, 0, v4, vcc
	v_bfe_u32 v6, v4, 16, 1
	v_add3_u32 v4, v4, v6, s33
	global_store_short_d16_hi v[2:3], v4, off offset:1536
	v_cndmask_b32_e64 v4, 0, 1, s[54:55]
	v_cndmask_b32_e64 v6, 0, 1, s[56:57]
	v_cndmask_b32_e64 v4, v6, v4, s[70:71]
	v_and_b32_e32 v4, 1, v4
	v_cmp_eq_u32_e32 vcc, 1, v4
	v_mul_f32_e32 v4, v0, v17
	s_add_i32 s89, s89, s78
	v_cndmask_b32_e32 v4, 0, v4, vcc
	v_bfe_u32 v6, v4, 16, 1
	v_add3_u32 v4, v4, v6, s33
	global_store_short_d16_hi v[2:3], v4, off offset:2048
	v_cndmask_b32_e64 v4, 0, 1, s[58:59]
	v_cndmask_b32_e64 v6, 0, 1, s[60:61]
	v_cndmask_b32_e64 v4, v6, v4, s[70:71]
	v_and_b32_e32 v4, 1, v4
	v_cmp_eq_u32_e32 vcc, 1, v4
	v_mul_f32_e32 v4, v0, v13
	v_readlane_b32 s77, v252, 18
	v_cndmask_b32_e32 v4, 0, v4, vcc
	v_bfe_u32 v6, v4, 16, 1
	v_add3_u32 v4, v4, v6, s33
	global_store_short_d16_hi v[2:3], v4, off offset:2560
	v_cndmask_b32_e64 v4, 0, 1, s[62:63]
	v_cndmask_b32_e64 v6, 0, 1, s[64:65]
	v_cndmask_b32_e64 v4, v6, v4, s[70:71]
	v_and_b32_e32 v4, 1, v4
	v_cmp_eq_u32_e32 vcc, 1, v4
	v_mul_f32_e32 v4, v0, v9
	v_mul_f32_e32 v0, v0, v5
	v_cndmask_b32_e32 v4, 0, v4, vcc
	v_bfe_u32 v6, v4, 16, 1
	v_add3_u32 v4, v4, v6, s33
	global_store_short_d16_hi v[2:3], v4, off offset:3072
	v_cndmask_b32_e64 v4, 0, 1, s[66:67]
	v_cndmask_b32_e64 v6, 0, 1, s[68:69]
	v_cndmask_b32_e64 v4, v6, v4, s[70:71]
	v_and_b32_e32 v4, 1, v4
	v_cmp_eq_u32_e32 vcc, 1, v4
	s_cmpk_gt_i32 s89, 0x1ff
	v_readlane_b32 s79, v252, 20
	v_cndmask_b32_e32 v0, 0, v0, vcc
	v_bfe_u32 v4, v0, 16, 1
	v_add3_u32 v0, v0, v4, s33
	global_store_short_d16_hi v[2:3], v0, off offset:3584
	s_cbranch_scc1 .LBB0_1163

.LBB0_1161:
	v_ashrrev_i32_e32 v4, 4, v3
	v_and_b32_e32 v7, 0x78, v2
	v_lshrrev_b32_e32 v8, 5, v4
	v_mul_u32_u24_e32 v8, 0x42, v8
	v_add_u32_e32 v8, s90, v8
	v_lshlrev_b32_e32 v8, 13, v8
	v_bfe_u32 v9, v4, 4, 1
	v_lshlrev_b32_e32 v9, 2, v9
	v_lshrrev_b32_e32 v10, 5, v7
	v_add_u32_e32 v9, v9, v10
	v_lshl_add_u32 v8, v9, 10, v8
	v_bfe_u32 v9, v7, 3, 2
	v_lshlrev_b32_e32 v9, 4, v9
	v_and_b32_e32 v10, 15, v4
	v_add_u32_e32 v9, v9, v10
	v_lshl_add_u32 v8, v9, 4, v8
	v_mov_b32_e32 v9, 0
	v_lshl_add_u64 v[8:9], s[98:99], 0, v[8:9]
	v_lshlrev_b32_e32 v0, 1, v4
	v_mul_u32_u24_e32 v4, 0x210, v7
	v_add3_u32 v0, 16, v0, v4
	s_movk_i32 s91, 0xdff
	s_mov_b32 s100, 0x84000
	s_mov_b32 s101, 0
	global_load_dwordx4 v[124:127], v[8:9], off
	v_lshl_add_u64 v[8:9], v[8:9], 0, s[100:101]
	global_load_dwordx4 v[128:131], v[8:9], off
	v_lshl_add_u64 v[8:9], v[8:9], 0, s[100:101]
	global_load_dwordx4 v[132:135], v[8:9], off
	v_lshl_add_u64 v[8:9], v[8:9], 0, s[100:101]
	global_load_dwordx4 v[136:139], v[8:9], off
	v_lshl_add_u64 v[8:9], v[8:9], 0, s[100:101]
	global_load_dwordx4 v[140:143], v[8:9], off
	v_lshl_add_u64 v[8:9], v[8:9], 0, s[100:101]
	global_load_dwordx4 v[144:147], v[8:9], off
	v_lshl_add_u64 v[8:9], v[8:9], 0, s[100:101]
	global_load_dwordx4 v[148:151], v[8:9], off
	v_lshl_add_u64 v[8:9], v[8:9], 0, s[100:101]
	global_load_dwordx4 v[152:155], v[8:9], off
	s_waitcnt vmcnt(7)
	ds_write_b16 v0, v124
	ds_write_b16_d16_hi v0, v124 offset:528
	ds_write_b16 v0, v125 offset:1056
	ds_write_b16_d16_hi v0, v125 offset:1584
	ds_write_b16 v0, v126 offset:2112
	ds_write_b16_d16_hi v0, v126 offset:2640
	ds_write_b16 v0, v127 offset:3168
	ds_write_b16_d16_hi v0, v127 offset:3696
	s_waitcnt vmcnt(6)
	ds_write_b16 v0, v128 offset:64
	ds_write_b16_d16_hi v0, v128 offset:592
	ds_write_b16 v0, v129 offset:1120
	ds_write_b16_d16_hi v0, v129 offset:1648
	ds_write_b16 v0, v130 offset:2176
	ds_write_b16_d16_hi v0, v130 offset:2704
	ds_write_b16 v0, v131 offset:3232
	ds_write_b16_d16_hi v0, v131 offset:3760
	s_waitcnt vmcnt(5)
	ds_write_b16 v0, v132 offset:128
	ds_write_b16_d16_hi v0, v132 offset:656
	ds_write_b16 v0, v133 offset:1184
	ds_write_b16_d16_hi v0, v133 offset:1712
	ds_write_b16 v0, v134 offset:2240
	ds_write_b16_d16_hi v0, v134 offset:2768
	ds_write_b16 v0, v135 offset:3296
	ds_write_b16_d16_hi v0, v135 offset:3824
	s_waitcnt vmcnt(4)
	ds_write_b16 v0, v136 offset:192
	ds_write_b16_d16_hi v0, v136 offset:720
	ds_write_b16 v0, v137 offset:1248
	ds_write_b16_d16_hi v0, v137 offset:1776
	ds_write_b16 v0, v138 offset:2304
	ds_write_b16_d16_hi v0, v138 offset:2832
	ds_write_b16 v0, v139 offset:3360
	ds_write_b16_d16_hi v0, v139 offset:3888
	s_waitcnt vmcnt(3)
	ds_write_b16 v0, v140 offset:256
	ds_write_b16_d16_hi v0, v140 offset:784
	ds_write_b16 v0, v141 offset:1312
	ds_write_b16_d16_hi v0, v141 offset:1840
	ds_write_b16 v0, v142 offset:2368
	ds_write_b16_d16_hi v0, v142 offset:2896
	ds_write_b16 v0, v143 offset:3424
	ds_write_b16_d16_hi v0, v143 offset:3952
	s_waitcnt vmcnt(2)
	ds_write_b16 v0, v144 offset:320
	ds_write_b16_d16_hi v0, v144 offset:848
	ds_write_b16 v0, v145 offset:1376
	ds_write_b16_d16_hi v0, v145 offset:1904
	ds_write_b16 v0, v146 offset:2432
	ds_write_b16_d16_hi v0, v146 offset:2960
	ds_write_b16 v0, v147 offset:3488
	ds_write_b16_d16_hi v0, v147 offset:4016
	s_waitcnt vmcnt(1)
	ds_write_b16 v0, v148 offset:384
	ds_write_b16_d16_hi v0, v148 offset:912
	ds_write_b16 v0, v149 offset:1440
	ds_write_b16_d16_hi v0, v149 offset:1968
	ds_write_b16 v0, v150 offset:2496
	ds_write_b16_d16_hi v0, v150 offset:3024
	ds_write_b16 v0, v151 offset:3552
	ds_write_b16_d16_hi v0, v151 offset:4080
	s_waitcnt vmcnt(0)
	ds_write_b16 v0, v152 offset:448
	ds_write_b16_d16_hi v0, v152 offset:976
	ds_write_b16 v0, v153 offset:1504
	ds_write_b16_d16_hi v0, v153 offset:2032
	ds_write_b16 v0, v154 offset:2560
	ds_write_b16_d16_hi v0, v154 offset:3088
	ds_write_b16 v0, v155 offset:3616
	ds_write_b16_d16_hi v0, v155 offset:4144
	s_or_b64 exec, exec, s[86:87]
	v_mov_b64_e32 v[4:5], s[72:73]
	v_mov_b64_e32 v[2:3], s[82:83]
	s_branch .LBB0_1156
